# adds: LUT copy loops unrolled (mixer A2/C), bias-LUT reads batched in mixer C non-edge loop, redundant lgkmcnt(0) after K-loop barriers removed
# speedup vs baseline: 1.0054x; 1.0032x over previous
; #define PG8_STAGE(bufoff, gbase, voff) do { _Pragma("unroll") for (int _i = 0; _i < 2; ++_i) \
;         __builtin_amdgcn_global_load_lds((const unsigned*)((const char*)(gbase) + (voff)[_i]), (PG8_LAS unsigned*)(lds + (bufoff) + ldsw + _i * 8192), 16, 0, 0); } while (0)
; #define PG8_LDA(dst, b, h) do { _Pragma("unroll") for (int m = 0; m < 4; ++m) _Pragma("unroll") for (int k = 0; k < 2; ++k) dst[m][k] = *(const PG8_LAS bf16x8*)(lds + PG8_SA(b, h) + aoff + m * 2048 + k * 1024); } while (0)
; #define PG8_LDB(dst, b, h) do { _Pragma("unroll") for (int n = 0; n < 2; ++n) _Pragma("unroll") for (int k = 0; k < 2; ++k) dst[n][k] = *(const PG8_LAS bf16x8*)(lds + PG8_SB(b, h) + boff + n * 2048 + k * 1024); } while (0)
; #define PG8_MMA(ai, bj, At, Bt) do { __builtin_amdgcn_s_setprio(1); _Pragma("unroll") for (int m = 0; m < 4; ++m) _Pragma("unroll") for (int n = 0; n < 2; ++n) _Pragma("unroll") for (int k = 0; k < 2; ++k) \
;         acc[ai][bj][m][n] = __builtin_amdgcn_mfma_f32_16x16x32_bf16(Bt[n][k], At[m][k], acc[ai][bj][m][n], 0, 0, 0); __builtin_amdgcn_s_setprio(0); } while (0)
; #define PG8_WAIT_V(n) asm volatile("s_waitcnt vmcnt(" #n ")" ::: "memory")
; #define PG8_WAIT_L(n) asm volatile("s_waitcnt lgkmcnt(" #n ")" ::: "memory")
; #define PG8_BAR __builtin_amdgcn_s_barrier()
; #define PG8_SCHED __builtin_amdgcn_sched_barrier(0)
; template <class Epi, class Sched, bool ALIGN_EPI = false, bool SP2 = false>
; __device__ __forceinline__ void gemm_phase(PG8_LAS unsigned char* lds, const Gemm g, const Sched& S, const Epi& E, int tid_in) {
;     ...
;             PG8_LDB(B0, 0, 0); PG8_LDB(B1, 0, 1); PG8_SCHED; PG8_LDA(At, 0, 0); PG8_STAGE(PG8_SA(1, 1), a1 + hstep, voffA);
;             PG8_WAIT_V(8); PG8_WAIT_L(0); PG8_BAR; PG8_MMA(0, 0, At, B0); PG8_MMA(0, 1, At, B1); PG8_BAR; PG8_SCHED;
;             PG8_LDA(At, 0, 1); PG8_STAGE(PG8_SB(0, 0), b2, voffB); PG8_STAGE(PG8_SB(0, 1), b2 + hstep, voffB); PG8_STAGE(PG8_SA(0, 0), a2, voffA);
;             PG8_WAIT_V(8); PG8_WAIT_L(0); PG8_BAR; PG8_MMA(1, 0, At, B0); PG8_MMA(1, 1, At, B1); PG8_BAR; PG8_SCHED;
.LBB0_151:
	s_add_i32 s36, s4, 2
	s_add_u32 s37, s0, 0x80
	s_addc_u32 s5, s1, 0
	s_add_i32 s90, 0, 0x10000
	s_cmp_eq_u32 s57, s4
	s_cselect_b32 s5, s39, s5
	s_cselect_b32 s4, s38, s37
	v_add_u32_e32 v144, s90, v151
	s_cselect_b32 s89, s45, s23
	s_cselect_b32 s88, s44, s22
	s_add_i32 s37, 0, 0x14000
	ds_read_b128 v[140:143], v144
	ds_read_b128 v[166:169], v144 offset:1024
	ds_read_b128 v[170:173], v144 offset:2048
	ds_read_b128 v[174:177], v144 offset:3072
	v_add_u32_e32 v144, s37, v151
	ds_read_b128 v[178:181], v144
	ds_read_b128 v[182:185], v144 offset:1024
	ds_read_b128 v[186:189], v144 offset:2048
	ds_read_b128 v[190:193], v144 offset:3072
	v_lshl_add_u64 v[144:145], s[0:1], 0, v[136:137]
	s_add_i32 m0, s43, 0xc000
	ds_read_b128 v[194:197], v161
	ds_read_b128 v[198:201], v161 offset:1024
	ds_read_b128 v[202:205], v161 offset:2048
	ds_read_b128 v[206:209], v161 offset:3072
	ds_read_b128 v[210:213], v161 offset:4096
	ds_read_b128 v[214:217], v161 offset:5120
	ds_read_b128 v[218:221], v161 offset:6144
	ds_read_b128 v[222:225], v161 offset:7168
	global_load_lds_dwordx4 v[144:145], off
	v_lshl_add_u64 v[144:145], s[0:1], 0, v[138:139]
	s_add_i32 m0, s43, 0xe000
	s_nop 0
	global_load_lds_dwordx4 v[144:145], off
	s_waitcnt vmcnt(8)
	s_waitcnt lgkmcnt(0)
	s_barrier
	s_setprio 1
	v_mfma_f32_16x16x32_bf16 v[124:127], v[140:143], v[194:197], v[124:127]
	v_mfma_f32_16x16x32_bf16 v[120:123], v[170:173], v[194:197], v[120:123]
	v_mfma_f32_16x16x32_bf16 v[108:111], v[140:143], v[202:205], v[108:111]
	v_mfma_f32_16x16x32_bf16 v[104:107], v[170:173], v[202:205], v[104:107]
	v_mfma_f32_16x16x32_bf16 v[92:95], v[140:143], v[210:213], v[92:95]
	v_mfma_f32_16x16x32_bf16 v[88:91], v[170:173], v[210:213], v[88:91]
	v_mfma_f32_16x16x32_bf16 v[76:79], v[140:143], v[218:221], v[76:79]
	v_mfma_f32_16x16x32_bf16 v[72:75], v[170:173], v[218:221], v[72:75]
	v_mfma_f32_16x16x32_bf16 v[124:127], v[166:169], v[198:201], v[124:127]
	v_mfma_f32_16x16x32_bf16 v[120:123], v[174:177], v[198:201], v[120:123]
	v_mfma_f32_16x16x32_bf16 v[108:111], v[166:169], v[206:209], v[108:111]
	v_mfma_f32_16x16x32_bf16 v[104:107], v[174:177], v[206:209], v[104:107]
	v_mfma_f32_16x16x32_bf16 v[92:95], v[166:169], v[214:217], v[92:95]
	v_mfma_f32_16x16x32_bf16 v[88:91], v[174:177], v[214:217], v[88:91]
	v_mfma_f32_16x16x32_bf16 v[76:79], v[166:169], v[222:225], v[76:79]
	v_mfma_f32_16x16x32_bf16 v[72:75], v[174:177], v[222:225], v[72:75]
	s_setprio 0
	s_setprio 1
	v_mfma_f32_16x16x32_bf16 v[116:119], v[178:181], v[194:197], v[116:119]
	v_mfma_f32_16x16x32_bf16 v[112:115], v[186:189], v[194:197], v[112:115]
	v_mfma_f32_16x16x32_bf16 v[100:103], v[178:181], v[202:205], v[100:103]
	v_mfma_f32_16x16x32_bf16 v[96:99], v[186:189], v[202:205], v[96:99]
	v_mfma_f32_16x16x32_bf16 v[84:87], v[178:181], v[210:213], v[84:87]
	v_mfma_f32_16x16x32_bf16 v[80:83], v[186:189], v[210:213], v[80:83]
	v_mfma_f32_16x16x32_bf16 v[68:71], v[178:181], v[218:221], v[68:71]
	v_mfma_f32_16x16x32_bf16 v[64:67], v[186:189], v[218:221], v[64:67]
	v_mfma_f32_16x16x32_bf16 v[116:119], v[182:185], v[198:201], v[116:119]
	v_mfma_f32_16x16x32_bf16 v[112:115], v[190:193], v[198:201], v[112:115]
	v_mfma_f32_16x16x32_bf16 v[100:103], v[182:185], v[206:209], v[100:103]
	v_mfma_f32_16x16x32_bf16 v[96:99], v[190:193], v[206:209], v[96:99]
	v_mfma_f32_16x16x32_bf16 v[84:87], v[182:185], v[214:217], v[84:87]
	v_mfma_f32_16x16x32_bf16 v[80:83], v[190:193], v[214:217], v[80:83]
	v_mfma_f32_16x16x32_bf16 v[68:71], v[182:185], v[222:225], v[68:71]
	v_mfma_f32_16x16x32_bf16 v[64:67], v[190:193], v[222:225], v[64:67]
	s_setprio 0
	s_barrier
	s_add_i32 s90, s90, s42
	v_lshl_add_u64 v[144:145], s[88:89], 0, v[156:157]
	s_mov_b32 m0, s90
	ds_read_b128 v[194:197], v161 offset:16384
	ds_read_b128 v[198:201], v161 offset:17408
	ds_read_b128 v[202:205], v161 offset:18432
	ds_read_b128 v[206:209], v161 offset:19456
	ds_read_b128 v[210:213], v161 offset:20480
	ds_read_b128 v[214:217], v161 offset:21504
	ds_read_b128 v[218:221], v161 offset:22528
	ds_read_b128 v[222:225], v161 offset:23552
	global_load_lds_dwordx4 v[144:145], off
	s_add_i32 m0, s90, 0x2000
	v_lshl_add_u64 v[226:227], s[88:89], 0, v[128:129]
	s_add_u32 s88, s88, s8
	s_addc_u32 s89, s89, s9
	s_add_i32 s37, s37, s42
	global_load_lds_dwordx4 v[226:227], off
	v_lshl_add_u64 v[228:229], s[88:89], 0, v[156:157]
	s_mov_b32 m0, s37
	v_lshl_add_u64 v[238:239], s[88:89], 0, v[128:129]
	global_load_lds_dwordx4 v[228:229], off
	s_add_i32 m0, s37, 0x2000
	v_lshl_add_u64 v[240:241], s[4:5], 0, v[132:133]
	global_load_lds_dwordx4 v[238:239], off
	s_mov_b32 m0, s43
	v_lshl_add_u64 v[242:243], s[4:5], 0, v[130:131]
	global_load_lds_dwordx4 v[240:241], off
	s_mov_b32 m0, s46
	s_nop 0
	global_load_lds_dwordx4 v[242:243], off
	s_waitcnt vmcnt(8)
	s_waitcnt lgkmcnt(0)
	s_barrier
; #define PG8_STAGE(bufoff, gbase, voff) do { _Pragma("unroll") for (int _i = 0; _i < 2; ++_i) \
;         __builtin_amdgcn_global_load_lds((const unsigned*)((const char*)(gbase) + (voff)[_i]), (PG8_LAS unsigned*)(lds + (bufoff) + ldsw + _i * 8192), 16, 0, 0); } while (0)
; #define PG8_LDA(dst, b, h) do { _Pragma("unroll") for (int m = 0; m < 4; ++m) _Pragma("unroll") for (int k = 0; k < 2; ++k) dst[m][k] = *(const PG8_LAS bf16x8*)(lds + PG8_SA(b, h) + aoff + m * 2048 + k * 1024); } while (0)
; #define PG8_LDB(dst, b, h) do { _Pragma("unroll") for (int n = 0; n < 2; ++n) _Pragma("unroll") for (int k = 0; k < 2; ++k) dst[n][k] = *(const PG8_LAS bf16x8*)(lds + PG8_SB(b, h) + boff + n * 2048 + k * 1024); } while (0)
; #define PG8_MMA(ai, bj, At, Bt) do { __builtin_amdgcn_s_setprio(1); _Pragma("unroll") for (int m = 0; m < 4; ++m) _Pragma("unroll") for (int n = 0; n < 2; ++n) _Pragma("unroll") for (int k = 0; k < 2; ++k) \
;         acc[ai][bj][m][n] = __builtin_amdgcn_mfma_f32_16x16x32_bf16(Bt[n][k], At[m][k], acc[ai][bj][m][n], 0, 0, 0); __builtin_amdgcn_s_setprio(0); } while (0)
; #define PG8_WAIT_V(n) asm volatile("s_waitcnt vmcnt(" #n ")" ::: "memory")
; #define PG8_WAIT_L(n) asm volatile("s_waitcnt lgkmcnt(" #n ")" ::: "memory")
; #define PG8_BAR __builtin_amdgcn_s_barrier()
; #define PG8_SCHED __builtin_amdgcn_sched_barrier(0)
; template <class Epi, class Sched, bool ALIGN_EPI = false, bool SP2 = false>
; __device__ __forceinline__ void gemm_phase(PG8_LAS unsigned char* lds, const Gemm g, const Sched& S, const Epi& E, int tid_in) {
;     ...
;             PG8_WAIT_V(8); PG8_WAIT_L(0); PG8_BAR; PG8_MMA(1, 0, At, B0); PG8_MMA(1, 1, At, B1); PG8_BAR; PG8_SCHED;
;             PG8_LDB(B0, 1, 0); PG8_LDB(B1, 1, 1); PG8_SCHED; PG8_LDA(At, 1, 0); PG8_STAGE(PG8_SA(0, 1), a2 + hstep, voffA);
;             PG8_WAIT_V(8); PG8_WAIT_L(0); PG8_BAR; PG8_MMA(0, 0, At, B0); PG8_MMA(0, 1, At, B1); PG8_BAR; PG8_SCHED;
	s_setprio 1
	v_mfma_f32_16x16x32_bf16 v[60:63], v[140:143], v[194:197], v[60:63]
	v_mfma_f32_16x16x32_bf16 v[56:59], v[170:173], v[194:197], v[56:59]
	v_mfma_f32_16x16x32_bf16 v[44:47], v[140:143], v[202:205], v[44:47]
	v_mfma_f32_16x16x32_bf16 v[40:43], v[170:173], v[202:205], v[40:43]
	v_mfma_f32_16x16x32_bf16 v[28:31], v[140:143], v[210:213], v[28:31]
	v_mfma_f32_16x16x32_bf16 v[24:27], v[170:173], v[210:213], v[24:27]
	v_mfma_f32_16x16x32_bf16 v[12:15], v[140:143], v[218:221], v[12:15]
	v_mfma_f32_16x16x32_bf16 v[8:11], v[170:173], v[218:221], v[8:11]
	v_mfma_f32_16x16x32_bf16 v[60:63], v[166:169], v[198:201], v[60:63]
	v_mfma_f32_16x16x32_bf16 v[56:59], v[174:177], v[198:201], v[56:59]
	v_mfma_f32_16x16x32_bf16 v[44:47], v[166:169], v[206:209], v[44:47]
	v_mfma_f32_16x16x32_bf16 v[40:43], v[174:177], v[206:209], v[40:43]
	v_mfma_f32_16x16x32_bf16 v[28:31], v[166:169], v[214:217], v[28:31]
	v_mfma_f32_16x16x32_bf16 v[24:27], v[174:177], v[214:217], v[24:27]
	v_mfma_f32_16x16x32_bf16 v[12:15], v[166:169], v[222:225], v[12:15]
	v_mfma_f32_16x16x32_bf16 v[8:11], v[174:177], v[222:225], v[8:11]
	s_setprio 0
	s_setprio 1
	v_mfma_f32_16x16x32_bf16 v[52:55], v[178:181], v[194:197], v[52:55]
	v_mfma_f32_16x16x32_bf16 v[48:51], v[186:189], v[194:197], v[48:51]
	v_mfma_f32_16x16x32_bf16 v[36:39], v[178:181], v[202:205], v[36:39]
	v_mfma_f32_16x16x32_bf16 v[32:35], v[186:189], v[202:205], v[32:35]
	v_mfma_f32_16x16x32_bf16 v[20:23], v[178:181], v[210:213], v[20:23]
	v_mfma_f32_16x16x32_bf16 v[16:19], v[186:189], v[210:213], v[16:19]
	v_mfma_f32_16x16x32_bf16 v[4:7], v[178:181], v[218:221], v[4:7]
	v_mfma_f32_16x16x32_bf16 v[0:3], v[186:189], v[218:221], v[0:3]
	v_mfma_f32_16x16x32_bf16 v[52:55], v[182:185], v[198:201], v[52:55]
	v_mfma_f32_16x16x32_bf16 v[48:51], v[190:193], v[198:201], v[48:51]
	v_mfma_f32_16x16x32_bf16 v[36:39], v[182:185], v[206:209], v[36:39]
	v_mfma_f32_16x16x32_bf16 v[32:35], v[190:193], v[206:209], v[32:35]
	v_mfma_f32_16x16x32_bf16 v[20:23], v[182:185], v[214:217], v[20:23]
	v_mfma_f32_16x16x32_bf16 v[16:19], v[190:193], v[214:217], v[16:19]
	v_mfma_f32_16x16x32_bf16 v[4:7], v[182:185], v[222:225], v[4:7]
	v_mfma_f32_16x16x32_bf16 v[0:3], v[190:193], v[222:225], v[0:3]
	s_setprio 0
	s_barrier
	s_add_i32 s37, 0, 0x18000
	v_add_u32_e32 v146, s37, v151
	s_add_i32 s88, 0, 0x1c000
	ds_read_b128 v[140:143], v146
	ds_read_b128 v[166:169], v146 offset:1024
	ds_read_b128 v[170:173], v146 offset:2048
	ds_read_b128 v[174:177], v146 offset:3072
	v_add_u32_e32 v146, s88, v151
	ds_read_b128 v[178:181], v146
	ds_read_b128 v[182:185], v146 offset:1024
	ds_read_b128 v[186:189], v146 offset:2048
	ds_read_b128 v[190:193], v146 offset:3072
	s_add_u32 s4, s4, s8
	s_addc_u32 s5, s5, s9
	s_mov_b32 m0, s47
	v_lshl_add_u64 v[244:245], s[4:5], 0, v[132:133]
	ds_read_b128 v[194:197], v161 offset:32768
	ds_read_b128 v[198:201], v161 offset:33792
	ds_read_b128 v[202:205], v161 offset:34816
	ds_read_b128 v[206:209], v161 offset:35840
	ds_read_b128 v[210:213], v161 offset:36864
	ds_read_b128 v[214:217], v161 offset:37888
	ds_read_b128 v[218:221], v161 offset:38912
	ds_read_b128 v[222:225], v161 offset:39936
	global_load_lds_dwordx4 v[244:245], off
	v_lshl_add_u64 v[244:245], s[4:5], 0, v[130:131]
	s_mov_b32 m0, s52
	s_nop 0
	global_load_lds_dwordx4 v[244:245], off
	s_waitcnt vmcnt(8)
	s_waitcnt lgkmcnt(0)
	s_barrier
	s_setprio 1
	v_mfma_f32_16x16x32_bf16 v[124:127], v[140:143], v[194:197], v[124:127]
	v_mfma_f32_16x16x32_bf16 v[120:123], v[170:173], v[194:197], v[120:123]
	v_mfma_f32_16x16x32_bf16 v[108:111], v[140:143], v[202:205], v[108:111]
	v_mfma_f32_16x16x32_bf16 v[104:107], v[170:173], v[202:205], v[104:107]
	v_mfma_f32_16x16x32_bf16 v[92:95], v[140:143], v[210:213], v[92:95]
	v_mfma_f32_16x16x32_bf16 v[88:91], v[170:173], v[210:213], v[88:91]
	v_mfma_f32_16x16x32_bf16 v[76:79], v[140:143], v[218:221], v[76:79]
	v_mfma_f32_16x16x32_bf16 v[72:75], v[170:173], v[218:221], v[72:75]
	v_mfma_f32_16x16x32_bf16 v[124:127], v[166:169], v[198:201], v[124:127]
	v_mfma_f32_16x16x32_bf16 v[120:123], v[174:177], v[198:201], v[120:123]
	v_mfma_f32_16x16x32_bf16 v[108:111], v[166:169], v[206:209], v[108:111]
	v_mfma_f32_16x16x32_bf16 v[104:107], v[174:177], v[206:209], v[104:107]
	v_mfma_f32_16x16x32_bf16 v[92:95], v[166:169], v[214:217], v[92:95]
	v_mfma_f32_16x16x32_bf16 v[88:91], v[174:177], v[214:217], v[88:91]
	v_mfma_f32_16x16x32_bf16 v[76:79], v[166:169], v[222:225], v[76:79]
	v_mfma_f32_16x16x32_bf16 v[72:75], v[174:177], v[222:225], v[72:75]
	s_setprio 0
	s_setprio 1
	v_mfma_f32_16x16x32_bf16 v[116:119], v[178:181], v[194:197], v[116:119]
	v_mfma_f32_16x16x32_bf16 v[112:115], v[186:189], v[194:197], v[112:115]
	v_mfma_f32_16x16x32_bf16 v[100:103], v[178:181], v[202:205], v[100:103]
	v_mfma_f32_16x16x32_bf16 v[96:99], v[186:189], v[202:205], v[96:99]
	v_mfma_f32_16x16x32_bf16 v[84:87], v[178:181], v[210:213], v[84:87]
	v_mfma_f32_16x16x32_bf16 v[80:83], v[186:189], v[210:213], v[80:83]
	v_mfma_f32_16x16x32_bf16 v[68:71], v[178:181], v[218:221], v[68:71]
	v_mfma_f32_16x16x32_bf16 v[64:67], v[186:189], v[218:221], v[64:67]
	v_mfma_f32_16x16x32_bf16 v[116:119], v[182:185], v[198:201], v[116:119]
	v_mfma_f32_16x16x32_bf16 v[112:115], v[190:193], v[198:201], v[112:115]
	v_mfma_f32_16x16x32_bf16 v[100:103], v[182:185], v[206:209], v[100:103]
	v_mfma_f32_16x16x32_bf16 v[96:99], v[190:193], v[206:209], v[96:99]
	v_mfma_f32_16x16x32_bf16 v[84:87], v[182:185], v[214:217], v[84:87]
	v_mfma_f32_16x16x32_bf16 v[80:83], v[190:193], v[214:217], v[80:83]
	v_mfma_f32_16x16x32_bf16 v[68:71], v[182:185], v[222:225], v[68:71]
	v_mfma_f32_16x16x32_bf16 v[64:67], v[190:193], v[222:225], v[64:67]
	s_setprio 0
	s_barrier
; #define PG8_STAGE(bufoff, gbase, voff) do { _Pragma("unroll") for (int _i = 0; _i < 2; ++_i) \
;         __builtin_amdgcn_global_load_lds((const unsigned*)((const char*)(gbase) + (voff)[_i]), (PG8_LAS unsigned*)(lds + (bufoff) + ldsw + _i * 8192), 16, 0, 0); } while (0)
; #define PG8_LDA(dst, b, h) do { _Pragma("unroll") for (int m = 0; m < 4; ++m) _Pragma("unroll") for (int k = 0; k < 2; ++k) dst[m][k] = *(const PG8_LAS bf16x8*)(lds + PG8_SA(b, h) + aoff + m * 2048 + k * 1024); } while (0)
; #define PG8_MMA(ai, bj, At, Bt) do { __builtin_amdgcn_s_setprio(1); _Pragma("unroll") for (int m = 0; m < 4; ++m) _Pragma("unroll") for (int n = 0; n < 2; ++n) _Pragma("unroll") for (int k = 0; k < 2; ++k) \
;         acc[ai][bj][m][n] = __builtin_amdgcn_mfma_f32_16x16x32_bf16(Bt[n][k], At[m][k], acc[ai][bj][m][n], 0, 0, 0); __builtin_amdgcn_s_setprio(0); } while (0)
; #define PG8_WAIT_V(n) asm volatile("s_waitcnt vmcnt(" #n ")" ::: "memory")
; #define PG8_WAIT_L(n) asm volatile("s_waitcnt lgkmcnt(" #n ")" ::: "memory")
; #define PG8_BAR __builtin_amdgcn_s_barrier()
; #define PG8_SCHED __builtin_amdgcn_sched_barrier(0)
; template <class Epi, class Sched, bool ALIGN_EPI = false, bool SP2 = false>
; __device__ __forceinline__ void gemm_phase(PG8_LAS unsigned char* lds, const Gemm g, const Sched& S, const Epi& E, int tid_in) {
;     ...
;         for (int t = 0; t < nt; t += 2) {
;             const bool last = (t == nt - 2);
;             const char* a1 = cA + (size_t)(t + 1) * kstep;
;             const char* a2 = last ? nA : cA + (size_t)(t + 2) * kstep; const char* b2 = last ? nB : cB + (size_t)(t + 2) * kstep;
;             const char* a3 = a2 + kstep; const char* b3 = b2 + kstep;
;     ...
;             PG8_LDA(At, 1, 1); PG8_STAGE(PG8_SB(1, 0), b3, voffB); PG8_STAGE(PG8_SB(1, 1), b3 + hstep, voffB); PG8_STAGE(PG8_SA(1, 0), a3, voffA);
;             PG8_WAIT_V(8); PG8_WAIT_L(0); PG8_BAR; PG8_MMA(1, 0, At, B0); PG8_MMA(1, 1, At, B1); PG8_BAR; PG8_SCHED;
	s_add_i32 s4, s37, s42
	v_lshl_add_u64 v[144:145], v[144:145], 0, s[64:65]
	s_mov_b32 m0, s4
	ds_read_b128 v[194:197], v161 offset:49152
	ds_read_b128 v[198:201], v161 offset:50176
	ds_read_b128 v[202:205], v161 offset:51200
	ds_read_b128 v[206:209], v161 offset:52224
	ds_read_b128 v[210:213], v161 offset:53248
	ds_read_b128 v[214:217], v161 offset:54272
	ds_read_b128 v[218:221], v161 offset:55296
	ds_read_b128 v[222:225], v161 offset:56320
	global_load_lds_dwordx4 v[144:145], off
	v_lshl_add_u64 v[144:145], v[226:227], 0, s[64:65]
	s_add_i32 m0, s4, 0x2000
	s_add_i32 s4, s88, s42
	global_load_lds_dwordx4 v[144:145], off
	v_lshl_add_u64 v[144:145], v[228:229], 0, s[64:65]
	s_mov_b32 m0, s4
	s_nop 0
	global_load_lds_dwordx4 v[144:145], off
	v_lshl_add_u64 v[144:145], v[238:239], 0, s[64:65]
	s_add_i32 m0, s4, 0x2000
	s_nop 0
	global_load_lds_dwordx4 v[144:145], off
	v_lshl_add_u64 v[144:145], v[240:241], 0, s[64:65]
	s_mov_b32 m0, s34
	s_nop 0
	global_load_lds_dwordx4 v[144:145], off
	v_lshl_add_u64 v[144:145], v[242:243], 0, s[64:65]
	s_mov_b32 m0, s35
	s_nop 0
	global_load_lds_dwordx4 v[144:145], off
	s_waitcnt vmcnt(8)
	s_waitcnt lgkmcnt(0)
	s_barrier
	s_setprio 1
	v_mfma_f32_16x16x32_bf16 v[60:63], v[140:143], v[194:197], v[60:63]
	v_mfma_f32_16x16x32_bf16 v[56:59], v[170:173], v[194:197], v[56:59]
	v_mfma_f32_16x16x32_bf16 v[44:47], v[140:143], v[202:205], v[44:47]
	v_mfma_f32_16x16x32_bf16 v[40:43], v[170:173], v[202:205], v[40:43]
	v_mfma_f32_16x16x32_bf16 v[28:31], v[140:143], v[210:213], v[28:31]
	v_mfma_f32_16x16x32_bf16 v[24:27], v[170:173], v[210:213], v[24:27]
	v_mfma_f32_16x16x32_bf16 v[12:15], v[140:143], v[218:221], v[12:15]
	v_mfma_f32_16x16x32_bf16 v[8:11], v[170:173], v[218:221], v[8:11]
	v_mfma_f32_16x16x32_bf16 v[60:63], v[166:169], v[198:201], v[60:63]
	v_mfma_f32_16x16x32_bf16 v[56:59], v[174:177], v[198:201], v[56:59]
	v_mfma_f32_16x16x32_bf16 v[44:47], v[166:169], v[206:209], v[44:47]
	v_mfma_f32_16x16x32_bf16 v[40:43], v[174:177], v[206:209], v[40:43]
	v_mfma_f32_16x16x32_bf16 v[28:31], v[166:169], v[214:217], v[28:31]
	v_mfma_f32_16x16x32_bf16 v[24:27], v[174:177], v[214:217], v[24:27]
	v_mfma_f32_16x16x32_bf16 v[12:15], v[166:169], v[222:225], v[12:15]
	v_mfma_f32_16x16x32_bf16 v[8:11], v[174:177], v[222:225], v[8:11]
	s_setprio 0
	s_setprio 1
	v_mfma_f32_16x16x32_bf16 v[52:55], v[178:181], v[194:197], v[52:55]
	v_mfma_f32_16x16x32_bf16 v[48:51], v[186:189], v[194:197], v[48:51]
	v_mfma_f32_16x16x32_bf16 v[36:39], v[178:181], v[202:205], v[36:39]
	v_mfma_f32_16x16x32_bf16 v[32:35], v[186:189], v[202:205], v[32:35]
	v_mfma_f32_16x16x32_bf16 v[20:23], v[178:181], v[210:213], v[20:23]
	v_mfma_f32_16x16x32_bf16 v[16:19], v[186:189], v[210:213], v[16:19]
	v_mfma_f32_16x16x32_bf16 v[4:7], v[178:181], v[218:221], v[4:7]
	v_mfma_f32_16x16x32_bf16 v[0:3], v[186:189], v[218:221], v[0:3]
	v_mfma_f32_16x16x32_bf16 v[52:55], v[182:185], v[198:201], v[52:55]
	v_mfma_f32_16x16x32_bf16 v[48:51], v[190:193], v[198:201], v[48:51]
	v_mfma_f32_16x16x32_bf16 v[36:39], v[182:185], v[206:209], v[36:39]
	v_mfma_f32_16x16x32_bf16 v[32:35], v[190:193], v[206:209], v[32:35]
	v_mfma_f32_16x16x32_bf16 v[20:23], v[182:185], v[214:217], v[20:23]
	v_mfma_f32_16x16x32_bf16 v[16:19], v[190:193], v[214:217], v[16:19]
	v_mfma_f32_16x16x32_bf16 v[4:7], v[182:185], v[222:225], v[4:7]
	v_mfma_f32_16x16x32_bf16 v[0:3], v[190:193], v[222:225], v[0:3]
	s_setprio 0
	s_barrier
	s_add_u32 s0, s0, 0x100
	s_addc_u32 s1, s1, 0
	s_add_u32 s22, s22, 0x100
	s_addc_u32 s23, s23, 0
	s_cmp_ge_i32 s36, s55
	s_mov_b32 s4, s36
	s_cbranch_scc0 .LBB0_151
	s_mov_b32 s88, 0x3a000000

; __device__ __forceinline__ float shx(float v, int mask, int lane) { return __builtin_bit_cast(float, __builtin_amdgcn_ds_bpermute((lane ^ mask) << 2, __builtin_bit_cast(int, v))); }
; #define LAS __attribute__((address_space(3)))
; __device__ __forceinline__ float ex2(float x) { return __builtin_amdgcn_exp2f(x); }
; #define MFMA16(a, b, c) __builtin_amdgcn_mfma_f32_16x16x32_bf16(a, b, c, 0, 0, 0)
; template <bool EDGE>
; __device__ __forceinline__ void tile_load(TileLd& L, const bf16_t* kp, const bf16_t* vp, int S, int pos0, int dil, int k0, int lane) {
;     asm volatile("" : "+s"(k0), "+s"(pos0));
;     const int i16 = lane & 15, quad = lane >> 4;
; #pragma unroll
;     for (int st = 0; st < 2; ++st) { int pos = pos0 + dil * (k0 + 16 * st + i16); if (EDGE) pos = min(max(pos, 0), S - 1);
;         const bf16_t* p = kp + (long)pos * NIN + quad * 8; L.k[st][0] = *(const bf16x8*)p; L.k[st][1] = *(const bf16x8*)(p + 32); }
; #pragma unroll
;     for (int i = 0; i < 4; ++i) { int pos = pos0 + dil * (k0 + 8 * i + (lane >> 3)); if (EDGE) pos = min(max(pos, 0), S - 1);
;         L.v[i] = *(const u32x4*)(vp + (long)pos * NIN + (lane & 7) * 8); }
; }
; template <int G, bool EDGE> ...
;     asm volatile("" : "+s"(k0));
;     const int quad = lane >> 4; const f32x4 z4 = {0.f, 0.f, 0.f, 0.f};
;     bf16x8 vf[4]; stage_v_regs(L.v, vimg, lane, vf);
;     constexpr float C2 = 0.125f * LOG2E, THR = 6.0f;
;     const int kb = k0 + 4 * quad;
; #pragma unroll
;     for (int g = 0; g < G; ++g) {
;         const LAS float* lutb = lut + (kb - ua[g] + R);
;         float sc[8]; float mx = -1e30f;
; #pragma unroll
;         for (int st = 0; st < 2; ++st) { f32x4 s = MFMA16(L.k[st][0], q[g][0], z4); s = MFMA16(L.k[st][1], q[g][1], s);
; #pragma unroll
;             for (int jj = 0; jj < 4; ++jj) { const int c = 16 * st + jj; const bool v = (unsigned)(kb - klo[g] + c) <= (unsigned)kspan[g];
;                 float x = s[jj] * C2 + lutb[g * lutstride + c]; x = v ? x : -1e30f; sc[4 * st + jj] = x; mx = fmaxf(mx, x); } }
;         if (__any(mx - m[g] > THR)) {
;             mx = fmaxf(mx, shx(mx, 16, lane)); mx = fmaxf(mx, shx(mx, 32, lane));
;             const float mn = fmaxf(m[g], mx), al = ex2(m[g] - mn); m[g] = mn; l[g] *= al;
; #pragma unroll
;             for (int nn = 0; nn < 4; ++nn) o[g][nn] = o[g][nn] * al;
.LBB0_609:
	s_sub_i32 s34, s1, 32
	s_mov_b32 s2, s52
	s_mov_b32 s3, s34
	s_add_i32 s4, s2, s3
	v_add_u32_e32 v54, s4, v199
	v_mad_i64_i32 v[52:53], s[2:3], v54, s97, v[144:145]
	v_add_u32_e32 v132, s4, v200
	global_load_dwordx4 v[68:71], v[52:53], off
	global_load_dwordx4 v[64:67], v[52:53], off offset:64
	v_add_u32_e32 v52, 16, v54
	v_mad_i64_i32 v[120:121], s[2:3], v132, s97, v[146:147]
	v_add_u32_e32 v124, 8, v132
	v_add_u32_e32 v128, 16, v132
	v_add_u32_e32 v132, 24, v132
	v_mad_i64_i32 v[56:57], s[2:3], v52, s97, v[144:145]
	v_mad_i64_i32 v[124:125], s[2:3], v124, s97, v[146:147]
	v_mad_i64_i32 v[128:129], s[2:3], v128, s97, v[146:147]
	v_mad_i64_i32 v[132:133], s[2:3], v132, s97, v[146:147]
	global_load_dwordx4 v[52:55], v[56:57], off
	s_nop 0
	global_load_dwordx4 v[56:59], v[56:57], off offset:64
	s_sub_i32 s2, s1, 64
	global_load_dwordx4 v[120:123], v[120:121], off
	v_add_u32_e32 v155, v202, v203
	global_load_dwordx4 v[124:127], v[124:125], off
	s_waitcnt vmcnt(13)
	v_mfma_f32_16x16x32_bf16 v[170:173], v[36:39], v[16:19], 0
	global_load_dwordx4 v[128:131], v[128:129], off
	s_nop 0
	global_load_dwordx4 v[132:135], v[132:133], off
	s_waitcnt vmcnt(11)
	ds_write_b128 v155, v[104:107]
	s_waitcnt vmcnt(10)
	ds_write_b128 v155, v[108:111] offset:1152
	s_waitcnt vmcnt(9)
	ds_write_b128 v155, v[112:115] offset:2304
	s_waitcnt vmcnt(8)
	ds_write_b128 v155, v[116:119] offset:3456
	v_add_u32_e32 v162, s2, v204
	v_sub_u32_e32 v163, v162, v199
	v_lshl_add_u32 v167, v163, 2, s22
	v_add_u32_e32 v226, 0x1400, v167
	ds_read2_b32 v[210:211], v226 offset0:0 offset1:1
	ds_read2_b32 v[212:213], v226 offset0:2 offset1:3
	ds_read2_b32 v[214:215], v226 offset0:16 offset1:17
	ds_read2_b32 v[216:217], v226 offset0:18 offset1:19
	v_add_u32_e32 v227, 0x1804, v167
	ds_read2_b32 v[218:219], v227 offset0:0 offset1:1
	ds_read2_b32 v[220:221], v227 offset0:2 offset1:3
	ds_read2_b32 v[222:223], v227 offset0:16 offset1:17
	ds_read2_b32 v[224:225], v227 offset0:18 offset1:19
	ds_read_b64_tr_b16 v[116:117], v205
	ds_read_b64_tr_b16 v[104:105], v205 offset:32
	ds_read_b64_tr_b16 v[118:119], v205 offset:2304
	ds_read_b64_tr_b16 v[106:107], v205 offset:2336
	ds_read_b64_tr_b16 v[108:109], v205 offset:64
	ds_read_b64_tr_b16 v[110:111], v205 offset:2368
	ds_read_b64_tr_b16 v[112:113], v205 offset:96
	ds_read_b64_tr_b16 v[114:115], v205 offset:2400
	v_sub_u32_e32 v178, v162, v139
	v_mfma_f32_16x16x32_bf16 v[170:173], v[32:35], v[20:23], v[170:173]
	v_cmp_gt_u32_e64 s[2:3], v178, v153
	s_waitcnt lgkmcnt(0)
	s_nop 5
	v_fmamk_f32 v162, v170, 0x3e38aa3b, v210
	v_cndmask_b32_e64 v169, v162, v235, s[2:3]
	v_add_u32_e32 v162, 1, v178
	v_cmp_gt_u32_e64 s[4:5], v162, v153
	v_add_u32_e32 v162, 2, v178
	v_fmac_f32_e32 v211, 0x3e38aa3b, v171
	v_cmp_gt_u32_e64 s[6:7], v162, v153
	v_cndmask_b32_e64 v170, v211, v235, s[4:5]
	v_max3_f32 v174, v169, s95, v170
	s_waitcnt lgkmcnt(0)
	v_fmamk_f32 v162, v172, 0x3e38aa3b, v212
	v_cndmask_b32_e64 v171, v162, v235, s[6:7]
	v_add_u32_e32 v162, 3, v178
	v_cmp_gt_u32_e64 s[8:9], v162, v153
	v_fmac_f32_e32 v213, 0x3e38aa3b, v173
	v_add_u32_e32 v162, 16, v178
	v_cndmask_b32_e64 v172, v213, v235, s[8:9]
	v_max3_f32 v179, v174, v171, v172
	v_mfma_f32_16x16x32_bf16 v[174:177], v[28:31], v[16:19], 0
	v_cmp_gt_u32_e64 s[10:11], v162, v153
	v_mfma_f32_16x16x32_bf16 v[174:177], v[24:27], v[20:23], v[174:177]
	s_waitcnt lgkmcnt(0)
	s_nop 6
	v_fmamk_f32 v162, v174, 0x3e38aa3b, v214
	v_cndmask_b32_e64 v173, v162, v235, s[10:11]
	v_add_u32_e32 v162, 17, v178
	v_cmp_gt_u32_e64 s[12:13], v162, v153
	v_add_u32_e32 v162, 18, v178
	v_fmac_f32_e32 v215, 0x3e38aa3b, v175
	v_cmp_gt_u32_e64 s[14:15], v162, v153
	v_cndmask_b32_e64 v174, v215, v235, s[12:13]
	v_max3_f32 v179, v179, v173, v174
	s_waitcnt lgkmcnt(0)
	v_fmamk_f32 v162, v176, 0x3e38aa3b, v216
	v_cndmask_b32_e64 v175, v162, v235, s[14:15]
	v_add_u32_e32 v162, 19, v178
	v_cmp_gt_u32_e64 s[16:17], v162, v153
	v_fmac_f32_e32 v217, 0x3e38aa3b, v177
	s_nop 0
	v_cndmask_b32_e64 v176, v217, v235, s[16:17]
	v_max3_f32 v177, v179, v175, v176
	v_sub_f32_e32 v162, v177, v150
	v_cmp_lt_f32_e32 vcc, s19, v162
	s_cbranch_vccz .LBB0_611
	ds_bpermute_b32 v162, v207, v177
	v_max_f32_e32 v163, v177, v177
	s_waitcnt lgkmcnt(0)
	v_max_f32_e32 v162, v162, v162
	v_max_f32_e32 v162, v163, v162
	ds_bpermute_b32 v163, v206, v162
	s_waitcnt lgkmcnt(0)
	v_max3_f32 v162, v150, v162, v163
	v_sub_f32_e32 v150, v150, v162
	v_exp_f32_e32 v150, v150
	s_nop 0
	v_mul_f32_e32 v161, v161, v150
	v_pk_mul_f32 v[102:103], v[102:103], v[150:151] op_sel_hi:[1,0]
	v_pk_mul_f32 v[100:101], v[100:101], v[150:151] op_sel_hi:[1,0]
	v_pk_mul_f32 v[94:95], v[94:95], v[150:151] op_sel_hi:[1,0]
	v_pk_mul_f32 v[92:93], v[92:93], v[150:151] op_sel_hi:[1,0]
	v_pk_mul_f32 v[90:91], v[90:91], v[150:151] op_sel_hi:[1,0]
	v_pk_mul_f32 v[88:89], v[88:89], v[150:151] op_sel_hi:[1,0]
	v_pk_mul_f32 v[98:99], v[98:99], v[150:151] op_sel_hi:[1,0]
	v_pk_mul_f32 v[96:97], v[96:97], v[150:151] op_sel_hi:[1,0]
	v_mov_b32_e32 v150, v162
; __device__ __forceinline__ float shx(float v, int mask, int lane) { return __builtin_bit_cast(float, __builtin_amdgcn_ds_bpermute((lane ^ mask) << 2, __builtin_bit_cast(int, v))); }
; __device__ __forceinline__ unsigned cvt_pk_vis(float lo, float hi) { const f32x2_t f = {lo, hi}; const bf16x2_t v = __builtin_convertvector(f, bf16x2_t); return __builtin_bit_cast(unsigned, v); }
; #define LAS __attribute__((address_space(3)))
; __device__ __forceinline__ float ex2(float x) { return __builtin_amdgcn_exp2f(x); }
; #define MFMA16(a, b, c) __builtin_amdgcn_mfma_f32_16x16x32_bf16(a, b, c, 0, 0, 0)
; template <int G, bool EDGE> ...
;     ...
;         const LAS float* lutb = lut + (kb - ua[g] + R);
;         float sc[8]; float mx = -1e30f;
; #pragma unroll
;         for (int st = 0; st < 2; ++st) { f32x4 s = MFMA16(L.k[st][0], q[g][0], z4); s = MFMA16(L.k[st][1], q[g][1], s);
; #pragma unroll
;             for (int jj = 0; jj < 4; ++jj) { const int c = 16 * st + jj; const bool v = (unsigned)(kb - klo[g] + c) <= (unsigned)kspan[g];
;                 float x = s[jj] * C2 + lutb[g * lutstride + c]; x = v ? x : -1e30f; sc[4 * st + jj] = x; mx = fmaxf(mx, x); } }
;         if (__any(mx - m[g] > THR)) {
;             mx = fmaxf(mx, shx(mx, 16, lane)); mx = fmaxf(mx, shx(mx, 32, lane));
;             const float mn = fmaxf(m[g], mx), al = ex2(m[g] - mn); m[g] = mn; l[g] *= al;
; #pragma unroll
;             for (int nn = 0; nn < 4; ++nn) o[g][nn] = o[g][nn] * al;
;         }
;         const float mn = m[g]; float p[8], ps = 0.f;
; #pragma unroll
;         for (int e = 0; e < 8; ++e) { p[e] = ex2(sc[e] - mn); ps += p[e]; }
;         l[g] += ps;
;         const u32x4 pw = {pg8::cvt_pk_vis(p[0], p[1]), pg8::cvt_pk_vis(p[2], p[3]), pg8::cvt_pk_vis(p[4], p[5]), pg8::cvt_pk_vis(p[6], p[7])}; const bf16x8 pf = __builtin_bit_cast(bf16x8, pw);
; #pragma unroll
;         for (int nn = 0; nn < 4; ++nn) o[g][nn] = MFMA16(vf[nn], pf, o[g][nn]);
.LBB0_611:
	v_sub_f32_e32 v162, v169, v150
	v_exp_f32_e32 v169, v162
	v_sub_f32_e32 v162, v170, v150
	v_exp_f32_e32 v170, v162
	v_sub_f32_e32 v162, v171, v150
	v_exp_f32_e32 v171, v162
	v_sub_f32_e32 v162, v172, v150
	v_exp_f32_e32 v172, v162
	v_sub_f32_e32 v162, v173, v150
	v_exp_f32_e32 v173, v162
	v_sub_f32_e32 v162, v174, v150
	v_exp_f32_e32 v174, v162
	v_sub_f32_e32 v162, v175, v150
	v_exp_f32_e32 v175, v162
	v_sub_f32_e32 v162, v176, v150
	v_exp_f32_e32 v176, v162
	v_cvt_pk_bf16_f32 v178, v169, v170
	v_cvt_pk_bf16_f32 v179, v171, v172
	v_cvt_pk_bf16_f32 v180, v173, v174
	v_cvt_pk_bf16_f32 v181, v175, v176
	s_nop 1
	v_mfma_f32_16x16x32_bf16 v[100:103], v[116:119], v[178:181], v[100:103]
	v_mfma_f32_16x16x32_bf16 v[92:95], v[104:107], v[178:181], v[92:95]
	v_mfma_f32_16x16x32_bf16 v[88:91], v[108:111], v[178:181], v[88:91]
	v_mfma_f32_16x16x32_bf16 v[96:99], v[112:115], v[178:181], v[96:99]
	v_mfma_f32_16x16x32_bf16 v[178:181], v[36:39], v[8:11], 0
	v_mfma_f32_16x16x32_bf16 v[178:181], v[32:35], v[12:15], v[178:181]
	s_waitcnt lgkmcnt(0)
	s_nop 6
	v_fmamk_f32 v162, v178, 0x3e38aa3b, v218
	v_cndmask_b32_e64 v177, v162, v235, s[2:3]
	v_fmac_f32_e32 v219, 0x3e38aa3b, v179
	v_cndmask_b32_e64 v178, v219, v235, s[4:5]
	v_max3_f32 v182, v177, s95, v178
	s_waitcnt lgkmcnt(0)
	v_fmamk_f32 v162, v180, 0x3e38aa3b, v220
	v_fmac_f32_e32 v221, 0x3e38aa3b, v181
	v_cndmask_b32_e64 v179, v162, v235, s[6:7]
	v_cndmask_b32_e64 v180, v221, v235, s[8:9]
	v_max3_f32 v186, v182, v179, v180
	v_mfma_f32_16x16x32_bf16 v[182:185], v[28:31], v[8:11], 0
	v_mfma_f32_16x16x32_bf16 v[182:185], v[24:27], v[12:15], v[182:185]
	s_waitcnt lgkmcnt(0)
	s_nop 6
	v_fmamk_f32 v162, v182, 0x3e38aa3b, v222
	v_cndmask_b32_e64 v181, v162, v235, s[10:11]
	v_fmac_f32_e32 v223, 0x3e38aa3b, v183
	v_cndmask_b32_e64 v182, v223, v235, s[12:13]
	v_max3_f32 v186, v186, v181, v182
	s_waitcnt lgkmcnt(0)
	v_fmamk_f32 v162, v184, 0x3e38aa3b, v224
	v_fmac_f32_e32 v225, 0x3e38aa3b, v185
	v_cndmask_b32_e64 v183, v162, v235, s[14:15]
	v_cndmask_b32_e64 v184, v225, v235, s[16:17]
	v_max3_f32 v185, v186, v183, v184
	v_sub_f32_e32 v162, v185, v143
	v_cmp_lt_f32_e32 vcc, s19, v162
	s_cbranch_vccz .LBB0_613
	ds_bpermute_b32 v162, v207, v185
	v_max_f32_e32 v163, v185, v185
	s_waitcnt lgkmcnt(0)
	v_max_f32_e32 v162, v162, v162
	v_max_f32_e32 v162, v163, v162
	ds_bpermute_b32 v163, v206, v162
	s_waitcnt lgkmcnt(0)
	v_max3_f32 v163, v143, v162, v163
	v_sub_f32_e32 v143, v143, v163
	v_exp_f32_e32 v162, v143
	v_mov_b32_e32 v143, v163
	v_mul_f32_e32 v154, v154, v162
	v_pk_mul_f32 v[78:79], v[78:79], v[162:163] op_sel_hi:[1,0]
	v_pk_mul_f32 v[76:77], v[76:77], v[162:163] op_sel_hi:[1,0]
	v_pk_mul_f32 v[74:75], v[74:75], v[162:163] op_sel_hi:[1,0]
	v_pk_mul_f32 v[72:73], v[72:73], v[162:163] op_sel_hi:[1,0]
	v_pk_mul_f32 v[82:83], v[82:83], v[162:163] op_sel_hi:[1,0]
	v_pk_mul_f32 v[80:81], v[80:81], v[162:163] op_sel_hi:[1,0]
	v_pk_mul_f32 v[86:87], v[86:87], v[162:163] op_sel_hi:[1,0]
	v_pk_mul_f32 v[84:85], v[84:85], v[162:163] op_sel_hi:[1,0]

; #define LAS __attribute__((address_space(3)))
; template <bool EDGE>
; __device__ __forceinline__ void tile_load(TileLd& L, const bf16_t* kp, const bf16_t* vp, int S, int pos0, int dil, int k0, int lane) {
;     asm volatile("" : "+s"(k0), "+s"(pos0));
;     const int i16 = lane & 15, quad = lane >> 4;
; #pragma unroll
;     for (int st = 0; st < 2; ++st) { int pos = pos0 + dil * (k0 + 16 * st + i16); if (EDGE) pos = min(max(pos, 0), S - 1);
;         const bf16_t* p = kp + (long)pos * NIN + quad * 8; L.k[st][0] = *(const bf16x8*)p; L.k[st][1] = *(const bf16x8*)(p + 32); }
; #pragma unroll
;     for (int i = 0; i < 4; ++i) { int pos = pos0 + dil * (k0 + 8 * i + (lane >> 3)); if (EDGE) pos = min(max(pos, 0), S - 1);
;         L.v[i] = *(const u32x4*)(vp + (long)pos * NIN + (lane & 7) * 8); }
; }
; template <int G, bool EDGE> ...
;     asm volatile("" : "+s"(k0));
;     const int quad = lane >> 4; const f32x4 z4 = {0.f, 0.f, 0.f, 0.f};
;     bf16x8 vf[4]; stage_v_regs(L.v, vimg, lane, vf);
;     constexpr float C2 = 0.125f * LOG2E, THR = 6.0f;
;     const int kb = k0 + 4 * quad;
; #pragma unroll
;     for (int g = 0; g < G; ++g) {
;         const LAS float* lutb = lut + (kb - ua[g] + R);
;         float sc[8]; float mx = -1e30f;
; #pragma unroll
;         for (int st = 0; st < 2; ++st) { f32x4 s = MFMA16(L.k[st][0], q[g][0], z4); s = MFMA16(L.k[st][1], q[g][1], s);
; #pragma unroll
;             for (int jj = 0; jj < 4; ++jj) { const int c = 16 * st + jj; const bool v = (unsigned)(kb - klo[g] + c) <= (unsigned)kspan[g];
;                 float x = s[jj] * C2 + lutb[g * lutstride + c]; x = v ? x : -1e30f; sc[4 * st + jj] = x; mx = fmaxf(mx, x); } }
;         if (__any(mx - m[g] > THR)) {
;             mx = fmaxf(mx, shx(mx, 16, lane)); mx = fmaxf(mx, shx(mx, 32, lane));
;             const float mn = fmaxf(m[g], mx), al = ex2(m[g] - mn); m[g] = mn; l[g] *= al;
; #pragma unroll
;             for (int nn = 0; nn < 4; ++nn) o[g][nn] = o[g][nn] * al;
;         }
;         const float mn = m[g]; float p[8], ps = 0.f;
; #pragma unroll
;         for (int e = 0; e < 8; ++e) { p[e] = ex2(sc[e] - mn); ps += p[e]; }
;         l[g] += ps;
;         const u32x4 pw = {pg8::cvt_pk_vis(p[0], p[1]), pg8::cvt_pk_vis(p[2], p[3]), pg8::cvt_pk_vis(p[4], p[5]), pg8::cvt_pk_vis(p[6], p[7])}; const bf16x8 pf = __builtin_bit_cast(bf16x8, pw);
; #pragma unroll
.LBB0_615:
	v_add_f32_e32 v29, 0, v169
	v_add_f32_e32 v29, v170, v29
	v_add_f32_e32 v29, v171, v29
	v_add_f32_e32 v29, v172, v29
	v_add_f32_e32 v29, v173, v29
	v_add_f32_e32 v29, v174, v29
	v_add_f32_e32 v29, v175, v29
	v_add_f32_e32 v29, v176, v29
	v_sub_f32_e32 v24, v24, v151
	v_add_f32_e32 v161, v161, v29
	v_sub_f32_e32 v29, v32, v151
	v_exp_f32_e32 v173, v24
	v_sub_f32_e32 v24, v25, v151
	v_exp_f32_e32 v169, v29
	v_sub_f32_e32 v29, v33, v151
	v_exp_f32_e32 v174, v24
	v_sub_f32_e32 v24, v26, v151
	v_exp_f32_e32 v170, v29
	v_sub_f32_e32 v29, v34, v151
	v_sub_f32_e32 v28, v28, v151
	v_exp_f32_e32 v175, v24
	v_sub_f32_e32 v24, v27, v151
	v_exp_f32_e32 v171, v29
	v_exp_f32_e32 v172, v28
	v_exp_f32_e32 v176, v24
	s_mov_b32 s2, s1
	s_mov_b32 s3, s52
	v_cvt_pk_bf16_f32 v24, v169, v170
	v_cvt_pk_bf16_f32 v25, v171, v172
	v_cvt_pk_bf16_f32 v26, v173, v174
	v_cvt_pk_bf16_f32 v27, v175, v176
	s_add_i32 s4, s3, s2
	s_waitcnt vmcnt(7)
	v_mfma_f32_16x16x32_bf16 v[186:189], v[68:71], v[16:19], 0
	v_mfma_f32_16x16x32_bf16 v[60:63], v[116:119], v[24:27], v[60:63]
	v_add_u32_e32 v116, s4, v200
	v_mfma_f32_16x16x32_bf16 v[48:51], v[104:107], v[24:27], v[48:51]
	v_mad_i64_i32 v[104:105], s[2:3], v116, s97, v[146:147]
	v_mfma_f32_16x16x32_bf16 v[44:47], v[108:111], v[24:27], v[44:47]
	v_add_u32_e32 v108, 8, v116
	v_mad_i64_i32 v[108:109], s[2:3], v108, s97, v[146:147]
	v_mfma_f32_16x16x32_bf16 v[40:43], v[112:115], v[24:27], v[40:43]
	v_add_u32_e32 v26, s4, v199
	v_mad_i64_i32 v[24:25], s[2:3], v26, s97, v[144:145]
	global_load_dwordx4 v[36:39], v[24:25], off
	global_load_dwordx4 v[32:35], v[24:25], off offset:64
	v_add_u32_e32 v24, 16, v26
	v_add_u32_e32 v112, 16, v116
	v_add_u32_e32 v116, 24, v116
	v_mad_i64_i32 v[24:25], s[2:3], v24, s97, v[144:145]
	v_mad_i64_i32 v[112:113], s[2:3], v112, s97, v[146:147]
	v_mad_i64_i32 v[116:117], s[2:3], v116, s97, v[146:147]
	global_load_dwordx4 v[28:31], v[24:25], off
	s_nop 0
	global_load_dwordx4 v[24:27], v[24:25], off offset:64
	s_waitcnt vmcnt(10)
	v_mfma_f32_16x16x32_bf16 v[186:189], v[64:67], v[20:23], v[186:189]
	global_load_dwordx4 v[104:107], v[104:105], off
	s_nop 0
	global_load_dwordx4 v[108:111], v[108:109], off
	s_nop 0
	global_load_dwordx4 v[112:115], v[112:113], off
	s_nop 0
	global_load_dwordx4 v[116:119], v[116:117], off
	s_waitcnt vmcnt(11)
	ds_write_b128 v155, v[120:123]
	s_waitcnt vmcnt(10)
	ds_write_b128 v155, v[124:127] offset:1152
	s_waitcnt vmcnt(9)
	ds_write_b128 v155, v[128:131] offset:2304
	s_waitcnt vmcnt(8)
	ds_write_b128 v155, v[132:135] offset:3456
	v_add_u32_e32 v162, s34, v204
	v_sub_u32_e32 v163, v162, v199
	v_lshl_add_u32 v167, v163, 2, s22
	v_add_u32_e32 v226, 0x1400, v167
	ds_read2_b32 v[210:211], v226 offset0:0 offset1:1
	ds_read2_b32 v[212:213], v226 offset0:2 offset1:3
	ds_read2_b32 v[214:215], v226 offset0:16 offset1:17
	ds_read2_b32 v[216:217], v226 offset0:18 offset1:19
	v_add_u32_e32 v227, 0x1804, v167
	ds_read2_b32 v[218:219], v227 offset0:0 offset1:1
	ds_read2_b32 v[220:221], v227 offset0:2 offset1:3
	ds_read2_b32 v[222:223], v227 offset0:16 offset1:17
	ds_read2_b32 v[224:225], v227 offset0:18 offset1:19
	ds_read_b64_tr_b16 v[124:125], v205
	ds_read_b64_tr_b16 v[120:121], v205 offset:32
	ds_read_b64_tr_b16 v[126:127], v205 offset:2304
	ds_read_b64_tr_b16 v[122:123], v205 offset:2336
	ds_read_b64_tr_b16 v[132:133], v205 offset:64
	ds_read_b64_tr_b16 v[134:135], v205 offset:2368
	ds_read_b64_tr_b16 v[128:129], v205 offset:96
	ds_read_b64_tr_b16 v[130:131], v205 offset:2400
	v_sub_u32_e32 v194, v162, v139
	v_cmp_gt_u32_e64 s[8:9], v194, v153
	s_waitcnt lgkmcnt(0)
	v_fmamk_f32 v162, v186, 0x3e38aa3b, v210
	v_cndmask_b32_e64 v185, v162, v235, s[8:9]
	v_add_u32_e32 v162, 1, v194
	v_cmp_gt_u32_e64 s[10:11], v162, v153
	v_add_u32_e32 v162, 2, v194
	v_fmac_f32_e32 v211, 0x3e38aa3b, v187
	v_cmp_gt_u32_e64 s[4:5], v162, v153
	v_cndmask_b32_e64 v186, v211, v235, s[10:11]
	v_max3_f32 v190, v185, s95, v186
	s_waitcnt lgkmcnt(0)
	v_fmamk_f32 v162, v188, 0x3e38aa3b, v212
	v_cndmask_b32_e64 v187, v162, v235, s[4:5]
	v_add_u32_e32 v162, 3, v194
	v_cmp_gt_u32_e64 s[12:13], v162, v153
	v_fmac_f32_e32 v213, 0x3e38aa3b, v189
	v_add_u32_e32 v162, 16, v194
	v_cndmask_b32_e64 v188, v213, v235, s[12:13]
	v_max3_f32 v195, v190, v187, v188
	v_mfma_f32_16x16x32_bf16 v[190:193], v[52:55], v[16:19], 0
	v_cmp_gt_u32_e64 s[6:7], v162, v153
	v_mfma_f32_16x16x32_bf16 v[190:193], v[56:59], v[20:23], v[190:193]
	s_waitcnt lgkmcnt(0)
	s_nop 6
	v_fmamk_f32 v162, v190, 0x3e38aa3b, v214
	v_cndmask_b32_e64 v189, v162, v235, s[6:7]
	v_add_u32_e32 v162, 17, v194
	v_cmp_gt_u32_e64 s[14:15], v162, v153
	v_add_u32_e32 v162, 18, v194
	v_fmac_f32_e32 v215, 0x3e38aa3b, v191
	v_cmp_gt_u32_e64 s[2:3], v162, v153
	v_cndmask_b32_e64 v190, v215, v235, s[14:15]
	v_max3_f32 v195, v195, v189, v190
	s_waitcnt lgkmcnt(0)
	v_fmamk_f32 v162, v192, 0x3e38aa3b, v216
	v_cndmask_b32_e64 v191, v162, v235, s[2:3]
	v_add_u32_e32 v162, 19, v194
	v_cmp_gt_u32_e64 s[16:17], v162, v153
	v_fmac_f32_e32 v217, 0x3e38aa3b, v193
	s_nop 0
	v_cndmask_b32_e64 v192, v217, v235, s[16:17]
	v_max3_f32 v193, v195, v191, v192
	v_sub_f32_e32 v162, v193, v150
	v_cmp_lt_f32_e32 vcc, s19, v162
	s_cbranch_vccz .LBB0_617
	ds_bpermute_b32 v162, v207, v193
	v_max_f32_e32 v163, v193, v193
	s_waitcnt lgkmcnt(0)
	v_max_f32_e32 v162, v162, v162
	v_max_f32_e32 v162, v163, v162
	ds_bpermute_b32 v163, v206, v162
	s_waitcnt lgkmcnt(0)
	v_max3_f32 v162, v150, v162, v163
	v_sub_f32_e32 v150, v150, v162
	v_exp_f32_e32 v150, v150
	s_nop 0
	v_mul_f32_e32 v161, v161, v150
	v_pk_mul_f32 v[102:103], v[102:103], v[150:151] op_sel_hi:[1,0]
	v_pk_mul_f32 v[100:101], v[100:101], v[150:151] op_sel_hi:[1,0]
	v_pk_mul_f32 v[94:95], v[94:95], v[150:151] op_sel_hi:[1,0]
	v_pk_mul_f32 v[92:93], v[92:93], v[150:151] op_sel_hi:[1,0]
	v_pk_mul_f32 v[90:91], v[90:91], v[150:151] op_sel_hi:[1,0]
	v_pk_mul_f32 v[88:89], v[88:89], v[150:151] op_sel_hi:[1,0]
	v_pk_mul_f32 v[98:99], v[98:99], v[150:151] op_sel_hi:[1,0]
	v_pk_mul_f32 v[96:97], v[96:97], v[150:151] op_sel_hi:[1,0]
	v_mov_b32_e32 v150, v162
; __device__ __forceinline__ float shx(float v, int mask, int lane) { return __builtin_bit_cast(float, __builtin_amdgcn_ds_bpermute((lane ^ mask) << 2, __builtin_bit_cast(int, v))); }
; __device__ __forceinline__ unsigned cvt_pk_vis(float lo, float hi) { const f32x2_t f = {lo, hi}; const bf16x2_t v = __builtin_convertvector(f, bf16x2_t); return __builtin_bit_cast(unsigned, v); }
; #define LAS __attribute__((address_space(3)))
; __device__ __forceinline__ float ex2(float x) { return __builtin_amdgcn_exp2f(x); }
; #define MFMA16(a, b, c) __builtin_amdgcn_mfma_f32_16x16x32_bf16(a, b, c, 0, 0, 0)
; template <int G, bool EDGE> ...
;     ...
;         const LAS float* lutb = lut + (kb - ua[g] + R);
;         float sc[8]; float mx = -1e30f;
; #pragma unroll
;         for (int st = 0; st < 2; ++st) { f32x4 s = MFMA16(L.k[st][0], q[g][0], z4); s = MFMA16(L.k[st][1], q[g][1], s);
; #pragma unroll
;             for (int jj = 0; jj < 4; ++jj) { const int c = 16 * st + jj; const bool v = (unsigned)(kb - klo[g] + c) <= (unsigned)kspan[g];
;                 float x = s[jj] * C2 + lutb[g * lutstride + c]; x = v ? x : -1e30f; sc[4 * st + jj] = x; mx = fmaxf(mx, x); } }
;         if (__any(mx - m[g] > THR)) {
;             mx = fmaxf(mx, shx(mx, 16, lane)); mx = fmaxf(mx, shx(mx, 32, lane));
;             const float mn = fmaxf(m[g], mx), al = ex2(m[g] - mn); m[g] = mn; l[g] *= al;
; #pragma unroll
;             for (int nn = 0; nn < 4; ++nn) o[g][nn] = o[g][nn] * al;
;         }
;         const float mn = m[g]; float p[8], ps = 0.f;
; #pragma unroll
;         for (int e = 0; e < 8; ++e) { p[e] = ex2(sc[e] - mn); ps += p[e]; }
;         l[g] += ps;
;         const u32x4 pw = {pg8::cvt_pk_vis(p[0], p[1]), pg8::cvt_pk_vis(p[2], p[3]), pg8::cvt_pk_vis(p[4], p[5]), pg8::cvt_pk_vis(p[6], p[7])}; const bf16x8 pf = __builtin_bit_cast(bf16x8, pw);
; #pragma unroll
;         for (int nn = 0; nn < 4; ++nn) o[g][nn] = MFMA16(vf[nn], pf, o[g][nn]);
.LBB0_617:
	v_add_f32_e32 v162, 0, v177
	v_add_f32_e32 v162, v178, v162
	v_add_f32_e32 v162, v179, v162
	v_add_f32_e32 v162, v180, v162
	v_add_f32_e32 v162, v181, v162
	v_add_f32_e32 v162, v182, v162
	v_add_f32_e32 v162, v183, v162
	v_add_f32_e32 v162, v184, v162
	v_add_f32_e32 v154, v154, v162
	v_sub_f32_e32 v162, v185, v150
	v_exp_f32_e32 v177, v162
	v_sub_f32_e32 v162, v186, v150
	v_exp_f32_e32 v178, v162
	v_sub_f32_e32 v162, v187, v150
	v_exp_f32_e32 v179, v162
	v_sub_f32_e32 v162, v188, v150
	v_exp_f32_e32 v180, v162
	v_sub_f32_e32 v162, v189, v150
	v_exp_f32_e32 v181, v162
	v_sub_f32_e32 v162, v190, v150
	v_exp_f32_e32 v182, v162
	v_sub_f32_e32 v162, v191, v150
	v_exp_f32_e32 v183, v162
	v_sub_f32_e32 v162, v192, v150
	v_exp_f32_e32 v184, v162
	v_cvt_pk_bf16_f32 v186, v177, v178
	v_cvt_pk_bf16_f32 v187, v179, v180
	v_cvt_pk_bf16_f32 v188, v181, v182
	v_cvt_pk_bf16_f32 v189, v183, v184
	s_nop 1
	v_mfma_f32_16x16x32_bf16 v[100:103], v[124:127], v[186:189], v[100:103]
	v_mfma_f32_16x16x32_bf16 v[92:95], v[120:123], v[186:189], v[92:95]
	v_mfma_f32_16x16x32_bf16 v[88:91], v[132:135], v[186:189], v[88:91]
	v_mfma_f32_16x16x32_bf16 v[96:99], v[128:131], v[186:189], v[96:99]
	v_mfma_f32_16x16x32_bf16 v[186:189], v[68:71], v[8:11], 0
	v_mfma_f32_16x16x32_bf16 v[186:189], v[64:67], v[12:15], v[186:189]
	s_waitcnt lgkmcnt(0)
	s_nop 6
	v_fmamk_f32 v162, v186, 0x3e38aa3b, v218
	v_cndmask_b32_e64 v185, v162, v235, s[8:9]
	v_fmac_f32_e32 v219, 0x3e38aa3b, v187
	v_cndmask_b32_e64 v186, v219, v235, s[10:11]
	v_max3_f32 v190, v185, s95, v186
	s_waitcnt lgkmcnt(0)
	v_fmamk_f32 v162, v188, 0x3e38aa3b, v220
	v_fmac_f32_e32 v221, 0x3e38aa3b, v189
	v_cndmask_b32_e64 v187, v162, v235, s[4:5]
	v_cndmask_b32_e64 v188, v221, v235, s[12:13]
	v_max3_f32 v194, v190, v187, v188
	v_mfma_f32_16x16x32_bf16 v[190:193], v[52:55], v[8:11], 0
	v_mfma_f32_16x16x32_bf16 v[190:193], v[56:59], v[12:15], v[190:193]
	s_waitcnt lgkmcnt(0)
	s_nop 6
	v_fmamk_f32 v162, v190, 0x3e38aa3b, v222
	v_cndmask_b32_e64 v189, v162, v235, s[6:7]
	v_fmac_f32_e32 v223, 0x3e38aa3b, v191
	v_cndmask_b32_e64 v190, v223, v235, s[14:15]
	v_max3_f32 v194, v194, v189, v190
	s_waitcnt lgkmcnt(0)
	v_fmamk_f32 v162, v192, 0x3e38aa3b, v224
	v_fmac_f32_e32 v225, 0x3e38aa3b, v193
	v_cndmask_b32_e64 v191, v162, v235, s[2:3]
	v_cndmask_b32_e64 v192, v225, v235, s[16:17]
	v_max3_f32 v193, v194, v191, v192
	v_sub_f32_e32 v162, v193, v143
	v_cmp_lt_f32_e32 vcc, s19, v162
	s_cbranch_vccz .LBB0_619
	ds_bpermute_b32 v162, v207, v193
	v_max_f32_e32 v163, v193, v193
	s_waitcnt lgkmcnt(0)
	v_max_f32_e32 v162, v162, v162
	v_max_f32_e32 v162, v163, v162
	ds_bpermute_b32 v163, v206, v162
	s_waitcnt lgkmcnt(0)
	v_max3_f32 v163, v143, v162, v163
	v_sub_f32_e32 v143, v143, v163
	v_exp_f32_e32 v162, v143
	v_mov_b32_e32 v143, v163
	v_mul_f32_e32 v154, v154, v162
	v_pk_mul_f32 v[78:79], v[78:79], v[162:163] op_sel_hi:[1,0]
	v_pk_mul_f32 v[76:77], v[76:77], v[162:163] op_sel_hi:[1,0]
	v_pk_mul_f32 v[74:75], v[74:75], v[162:163] op_sel_hi:[1,0]
	v_pk_mul_f32 v[72:73], v[72:73], v[162:163] op_sel_hi:[1,0]
	v_pk_mul_f32 v[82:83], v[82:83], v[162:163] op_sel_hi:[1,0]
	v_pk_mul_f32 v[80:81], v[80:81], v[162:163] op_sel_hi:[1,0]
	v_pk_mul_f32 v[86:87], v[86:87], v[162:163] op_sel_hi:[1,0]
	v_pk_mul_f32 v[84:85], v[84:85], v[162:163] op_sel_hi:[1,0]

; #define PG8_STAGE(bufoff, gbase, voff) do { _Pragma("unroll") for (int _i = 0; _i < 2; ++_i) \
;         __builtin_amdgcn_global_load_lds((const unsigned*)((const char*)(gbase) + (voff)[_i]), (PG8_LAS unsigned*)(lds + (bufoff) + ldsw + _i * 8192), 16, 0, 0); } while (0)
; #define PG8_LDA(dst, b, h) do { _Pragma("unroll") for (int m = 0; m < 4; ++m) _Pragma("unroll") for (int k = 0; k < 2; ++k) dst[m][k] = *(const PG8_LAS bf16x8*)(lds + PG8_SA(b, h) + aoff + m * 2048 + k * 1024); } while (0)
; #define PG8_LDB(dst, b, h) do { _Pragma("unroll") for (int n = 0; n < 2; ++n) _Pragma("unroll") for (int k = 0; k < 2; ++k) dst[n][k] = *(const PG8_LAS bf16x8*)(lds + PG8_SB(b, h) + boff + n * 2048 + k * 1024); } while (0)
; #define PG8_MMA(ai, bj, At, Bt) do { __builtin_amdgcn_s_setprio(1); _Pragma("unroll") for (int m = 0; m < 4; ++m) _Pragma("unroll") for (int n = 0; n < 2; ++n) _Pragma("unroll") for (int k = 0; k < 2; ++k) \
;         acc[ai][bj][m][n] = __builtin_amdgcn_mfma_f32_16x16x32_bf16(Bt[n][k], At[m][k], acc[ai][bj][m][n], 0, 0, 0); __builtin_amdgcn_s_setprio(0); } while (0)
; #define PG8_WAIT_V(n) asm volatile("s_waitcnt vmcnt(" #n ")" ::: "memory")
; #define PG8_WAIT_L(n) asm volatile("s_waitcnt lgkmcnt(" #n ")" ::: "memory")
; #define PG8_BAR __builtin_amdgcn_s_barrier()
; #define PG8_SCHED __builtin_amdgcn_sched_barrier(0)
; template <class Epi, class Sched, bool ALIGN_EPI = false, bool SP2 = false>
; __device__ __forceinline__ void gemm_phase(PG8_LAS unsigned char* lds, const Gemm g, const Sched& S, const Epi& E, int tid_in) {
;     ...
;             PG8_LDB(B0, 0, 0); PG8_LDB(B1, 0, 1); PG8_SCHED; PG8_LDA(At, 0, 0); PG8_STAGE(PG8_SA(1, 1), a1 + hstep, voffA);
;             PG8_WAIT_V(8); PG8_WAIT_L(0); PG8_BAR; PG8_MMA(0, 0, At, B0); PG8_MMA(0, 1, At, B1); PG8_BAR; PG8_SCHED;
;             PG8_LDA(At, 0, 1); PG8_STAGE(PG8_SB(0, 0), b2, voffB); PG8_STAGE(PG8_SB(0, 1), b2 + hstep, voffB); PG8_STAGE(PG8_SA(0, 0), a2, voffA);
;             PG8_WAIT_V(8); PG8_WAIT_L(0); PG8_BAR; PG8_MMA(1, 0, At, B0); PG8_MMA(1, 1, At, B1); PG8_BAR; PG8_SCHED;
.LBB0_820:
	s_add_i32 s36, s22, 2
	s_add_u32 s2, s0, 0x80
	s_addc_u32 s3, s1, 0
	s_add_i32 s37, 0, 0x10000
	s_cmp_eq_u32 s90, s22
	s_cselect_b32 s23, s9, s3
	s_cselect_b32 s22, s8, s2
	s_cselect_b32 s3, s55, vcc_lo
	s_cselect_b32 s2, s54, s63
	s_add_i32 vcc_hi, 0, 0x14000
	v_add_u32_e32 v146, s37, v237
	v_add_u32_e32 v154, vcc_hi, v237
	ds_read_b128 v[134:137], v146
	ds_read_b128 v[138:141], v146 offset:1024
	ds_read_b128 v[142:145], v146 offset:2048
	ds_read_b128 v[146:149], v146 offset:3072
	ds_read_b128 v[150:153], v154
	ds_read_b128 v[166:169], v154 offset:1024
	ds_read_b128 v[170:173], v154 offset:2048
	ds_read_b128 v[174:177], v154 offset:3072
	v_lshl_add_u64 v[154:155], s[0:1], 0, v[130:131]
	s_add_i32 m0, s47, 0xc000
	ds_read_b128 v[178:181], v241
	ds_read_b128 v[182:185], v241 offset:1024
	ds_read_b128 v[186:189], v241 offset:2048
	ds_read_b128 v[190:193], v241 offset:3072
	ds_read_b128 v[194:197], v241 offset:4096
	ds_read_b128 v[198:201], v241 offset:5120
	ds_read_b128 v[202:205], v241 offset:6144
	ds_read_b128 v[206:209], v241 offset:7168
	global_load_lds_dwordx4 v[154:155], off
	v_lshl_add_u64 v[154:155], s[0:1], 0, v[132:133]
	s_add_i32 m0, s47, 0xe000
	s_nop 0
	global_load_lds_dwordx4 v[154:155], off
	s_waitcnt vmcnt(8)
	s_waitcnt lgkmcnt(0)
	s_barrier
	s_setprio 1
	v_mfma_f32_16x16x32_bf16 v[124:127], v[134:137], v[178:181], v[124:127]
	v_mfma_f32_16x16x32_bf16 v[120:123], v[142:145], v[178:181], v[120:123]
	v_mfma_f32_16x16x32_bf16 v[108:111], v[134:137], v[186:189], v[108:111]
	v_mfma_f32_16x16x32_bf16 v[104:107], v[142:145], v[186:189], v[104:107]
	v_mfma_f32_16x16x32_bf16 v[92:95], v[134:137], v[194:197], v[92:95]
	v_mfma_f32_16x16x32_bf16 v[88:91], v[142:145], v[194:197], v[88:91]
	v_mfma_f32_16x16x32_bf16 v[76:79], v[134:137], v[202:205], v[76:79]
	v_mfma_f32_16x16x32_bf16 v[72:75], v[142:145], v[202:205], v[72:75]
	v_mfma_f32_16x16x32_bf16 v[124:127], v[138:141], v[182:185], v[124:127]
	v_mfma_f32_16x16x32_bf16 v[120:123], v[146:149], v[182:185], v[120:123]
	v_mfma_f32_16x16x32_bf16 v[108:111], v[138:141], v[190:193], v[108:111]
	v_mfma_f32_16x16x32_bf16 v[104:107], v[146:149], v[190:193], v[104:107]
	v_mfma_f32_16x16x32_bf16 v[92:95], v[138:141], v[198:201], v[92:95]
	v_mfma_f32_16x16x32_bf16 v[88:91], v[146:149], v[198:201], v[88:91]
	v_mfma_f32_16x16x32_bf16 v[76:79], v[138:141], v[206:209], v[76:79]
	v_mfma_f32_16x16x32_bf16 v[72:75], v[146:149], v[206:209], v[72:75]
	s_setprio 0
	s_setprio 1
	v_mfma_f32_16x16x32_bf16 v[116:119], v[150:153], v[178:181], v[116:119]
	v_mfma_f32_16x16x32_bf16 v[112:115], v[170:173], v[178:181], v[112:115]
	v_mfma_f32_16x16x32_bf16 v[100:103], v[150:153], v[186:189], v[100:103]
	v_mfma_f32_16x16x32_bf16 v[96:99], v[170:173], v[186:189], v[96:99]
	v_mfma_f32_16x16x32_bf16 v[84:87], v[150:153], v[194:197], v[84:87]
	v_mfma_f32_16x16x32_bf16 v[80:83], v[170:173], v[194:197], v[80:83]
	v_mfma_f32_16x16x32_bf16 v[68:71], v[150:153], v[202:205], v[68:71]
	v_mfma_f32_16x16x32_bf16 v[64:67], v[170:173], v[202:205], v[64:67]
	v_mfma_f32_16x16x32_bf16 v[116:119], v[166:169], v[182:185], v[116:119]
	v_mfma_f32_16x16x32_bf16 v[112:115], v[174:177], v[182:185], v[112:115]
	v_mfma_f32_16x16x32_bf16 v[100:103], v[166:169], v[190:193], v[100:103]
	v_mfma_f32_16x16x32_bf16 v[96:99], v[174:177], v[190:193], v[96:99]
	v_mfma_f32_16x16x32_bf16 v[84:87], v[166:169], v[198:201], v[84:87]
	v_mfma_f32_16x16x32_bf16 v[80:83], v[174:177], v[198:201], v[80:83]
	v_mfma_f32_16x16x32_bf16 v[68:71], v[166:169], v[206:209], v[68:71]
	v_mfma_f32_16x16x32_bf16 v[64:67], v[174:177], v[206:209], v[64:67]
	s_setprio 0
	s_barrier
	s_add_i32 s37, s37, s46
	v_lshl_add_u64 v[154:155], s[2:3], 0, v[156:157]
	s_mov_b32 m0, s37
	ds_read_b128 v[178:181], v241 offset:16384
	ds_read_b128 v[182:185], v241 offset:17408
	ds_read_b128 v[186:189], v241 offset:18432
	ds_read_b128 v[190:193], v241 offset:19456
	ds_read_b128 v[194:197], v241 offset:20480
	ds_read_b128 v[198:201], v241 offset:21504
	ds_read_b128 v[202:205], v241 offset:22528
	ds_read_b128 v[206:209], v241 offset:23552
	global_load_lds_dwordx4 v[154:155], off
	s_add_i32 m0, s37, 0x2000
	v_lshl_add_u64 v[162:163], s[2:3], 0, v[128:129]
	s_add_u32 s2, s2, s12
	s_addc_u32 s3, s3, s13
	s_add_i32 s37, vcc_hi, s46
	global_load_lds_dwordx4 v[162:163], off
	v_lshl_add_u64 v[210:211], s[2:3], 0, v[156:157]
	s_mov_b32 m0, s37
	v_lshl_add_u64 v[212:213], s[2:3], 0, v[128:129]
	global_load_lds_dwordx4 v[210:211], off
	s_add_i32 m0, s37, 0x2000
	v_lshl_add_u64 v[214:215], s[22:23], 0, v[156:157]
	global_load_lds_dwordx4 v[212:213], off
	s_mov_b32 m0, s47
	v_lshl_add_u64 v[216:217], s[22:23], 0, v[128:129]
	global_load_lds_dwordx4 v[214:215], off
	s_mov_b32 m0, s52
	s_nop 0
	global_load_lds_dwordx4 v[216:217], off
	s_waitcnt vmcnt(8)
	s_waitcnt lgkmcnt(0)
	s_barrier
; #define PG8_STAGE(bufoff, gbase, voff) do { _Pragma("unroll") for (int _i = 0; _i < 2; ++_i) \
;         __builtin_amdgcn_global_load_lds((const unsigned*)((const char*)(gbase) + (voff)[_i]), (PG8_LAS unsigned*)(lds + (bufoff) + ldsw + _i * 8192), 16, 0, 0); } while (0)
; #define PG8_LDA(dst, b, h) do { _Pragma("unroll") for (int m = 0; m < 4; ++m) _Pragma("unroll") for (int k = 0; k < 2; ++k) dst[m][k] = *(const PG8_LAS bf16x8*)(lds + PG8_SA(b, h) + aoff + m * 2048 + k * 1024); } while (0)
; #define PG8_LDB(dst, b, h) do { _Pragma("unroll") for (int n = 0; n < 2; ++n) _Pragma("unroll") for (int k = 0; k < 2; ++k) dst[n][k] = *(const PG8_LAS bf16x8*)(lds + PG8_SB(b, h) + boff + n * 2048 + k * 1024); } while (0)
; #define PG8_MMA(ai, bj, At, Bt) do { __builtin_amdgcn_s_setprio(1); _Pragma("unroll") for (int m = 0; m < 4; ++m) _Pragma("unroll") for (int n = 0; n < 2; ++n) _Pragma("unroll") for (int k = 0; k < 2; ++k) \
;         acc[ai][bj][m][n] = __builtin_amdgcn_mfma_f32_16x16x32_bf16(Bt[n][k], At[m][k], acc[ai][bj][m][n], 0, 0, 0); __builtin_amdgcn_s_setprio(0); } while (0)
; #define PG8_WAIT_V(n) asm volatile("s_waitcnt vmcnt(" #n ")" ::: "memory")
; #define PG8_WAIT_L(n) asm volatile("s_waitcnt lgkmcnt(" #n ")" ::: "memory")
; #define PG8_BAR __builtin_amdgcn_s_barrier()
; #define PG8_SCHED __builtin_amdgcn_sched_barrier(0)
; template <class Epi, class Sched, bool ALIGN_EPI = false, bool SP2 = false>
; __device__ __forceinline__ void gemm_phase(PG8_LAS unsigned char* lds, const Gemm g, const Sched& S, const Epi& E, int tid_in) {
;     ...
;             PG8_WAIT_V(8); PG8_WAIT_L(0); PG8_BAR; PG8_MMA(1, 0, At, B0); PG8_MMA(1, 1, At, B1); PG8_BAR; PG8_SCHED;
;             PG8_LDB(B0, 1, 0); PG8_LDB(B1, 1, 1); PG8_SCHED; PG8_LDA(At, 1, 0); PG8_STAGE(PG8_SA(0, 1), a2 + hstep, voffA);
;             PG8_WAIT_V(8); PG8_WAIT_L(0); PG8_BAR; PG8_MMA(0, 0, At, B0); PG8_MMA(0, 1, At, B1); PG8_BAR; PG8_SCHED;
	s_setprio 1
	v_mfma_f32_16x16x32_bf16 v[60:63], v[134:137], v[178:181], v[60:63]
	v_mfma_f32_16x16x32_bf16 v[56:59], v[142:145], v[178:181], v[56:59]
	v_mfma_f32_16x16x32_bf16 v[44:47], v[134:137], v[186:189], v[44:47]
	v_mfma_f32_16x16x32_bf16 v[40:43], v[142:145], v[186:189], v[40:43]
	v_mfma_f32_16x16x32_bf16 v[28:31], v[134:137], v[194:197], v[28:31]
	v_mfma_f32_16x16x32_bf16 v[24:27], v[142:145], v[194:197], v[24:27]
	v_mfma_f32_16x16x32_bf16 v[12:15], v[134:137], v[202:205], v[12:15]
	v_mfma_f32_16x16x32_bf16 v[8:11], v[142:145], v[202:205], v[8:11]
	v_mfma_f32_16x16x32_bf16 v[60:63], v[138:141], v[182:185], v[60:63]
	v_mfma_f32_16x16x32_bf16 v[56:59], v[146:149], v[182:185], v[56:59]
	v_mfma_f32_16x16x32_bf16 v[44:47], v[138:141], v[190:193], v[44:47]
	v_mfma_f32_16x16x32_bf16 v[40:43], v[146:149], v[190:193], v[40:43]
	v_mfma_f32_16x16x32_bf16 v[28:31], v[138:141], v[198:201], v[28:31]
	v_mfma_f32_16x16x32_bf16 v[24:27], v[146:149], v[198:201], v[24:27]
	v_mfma_f32_16x16x32_bf16 v[12:15], v[138:141], v[206:209], v[12:15]
	v_mfma_f32_16x16x32_bf16 v[8:11], v[146:149], v[206:209], v[8:11]
	s_setprio 0
	s_setprio 1
	v_mfma_f32_16x16x32_bf16 v[52:55], v[150:153], v[178:181], v[52:55]
	v_mfma_f32_16x16x32_bf16 v[48:51], v[170:173], v[178:181], v[48:51]
	v_mfma_f32_16x16x32_bf16 v[36:39], v[150:153], v[186:189], v[36:39]
	v_mfma_f32_16x16x32_bf16 v[32:35], v[170:173], v[186:189], v[32:35]
	v_mfma_f32_16x16x32_bf16 v[20:23], v[150:153], v[194:197], v[20:23]
	v_mfma_f32_16x16x32_bf16 v[16:19], v[170:173], v[194:197], v[16:19]
	v_mfma_f32_16x16x32_bf16 v[4:7], v[150:153], v[202:205], v[4:7]
	v_mfma_f32_16x16x32_bf16 v[0:3], v[170:173], v[202:205], v[0:3]
	v_mfma_f32_16x16x32_bf16 v[52:55], v[166:169], v[182:185], v[52:55]
	v_mfma_f32_16x16x32_bf16 v[48:51], v[174:177], v[182:185], v[48:51]
	v_mfma_f32_16x16x32_bf16 v[36:39], v[166:169], v[190:193], v[36:39]
	v_mfma_f32_16x16x32_bf16 v[32:35], v[174:177], v[190:193], v[32:35]
	v_mfma_f32_16x16x32_bf16 v[20:23], v[166:169], v[198:201], v[20:23]
	v_mfma_f32_16x16x32_bf16 v[16:19], v[174:177], v[198:201], v[16:19]
	v_mfma_f32_16x16x32_bf16 v[4:7], v[166:169], v[206:209], v[4:7]
	v_mfma_f32_16x16x32_bf16 v[0:3], v[174:177], v[206:209], v[0:3]
	s_setprio 0
	s_barrier
	s_add_i32 s37, 0, 0x18000
	s_add_i32 vcc_hi, 0, 0x1c000
	v_add_u32_e32 v146, s37, v237
	v_add_u32_e32 v174, vcc_hi, v237
	ds_read_b128 v[134:137], v146
	ds_read_b128 v[138:141], v146 offset:1024
	ds_read_b128 v[142:145], v146 offset:2048
	ds_read_b128 v[146:149], v146 offset:3072
	ds_read_b128 v[150:153], v174
	ds_read_b128 v[166:169], v174 offset:1024
	ds_read_b128 v[170:173], v174 offset:2048
	ds_read_b128 v[174:177], v174 offset:3072
	s_add_u32 s2, s22, s12
	s_addc_u32 s3, s23, s13
	s_mov_b32 m0, s53
	v_lshl_add_u64 v[218:219], s[2:3], 0, v[156:157]
	ds_read_b128 v[178:181], v241 offset:32768
	ds_read_b128 v[182:185], v241 offset:33792
	ds_read_b128 v[186:189], v241 offset:34816
	ds_read_b128 v[190:193], v241 offset:35840
	ds_read_b128 v[194:197], v241 offset:36864
	ds_read_b128 v[198:201], v241 offset:37888
	ds_read_b128 v[202:205], v241 offset:38912
	ds_read_b128 v[206:209], v241 offset:39936
	global_load_lds_dwordx4 v[218:219], off
	v_lshl_add_u64 v[218:219], s[2:3], 0, v[128:129]
	s_mov_b32 m0, s56
	s_nop 0
	global_load_lds_dwordx4 v[218:219], off
	s_waitcnt vmcnt(8)
	s_waitcnt lgkmcnt(0)
	s_barrier
	s_setprio 1
	v_mfma_f32_16x16x32_bf16 v[124:127], v[134:137], v[178:181], v[124:127]
	v_mfma_f32_16x16x32_bf16 v[120:123], v[142:145], v[178:181], v[120:123]
	v_mfma_f32_16x16x32_bf16 v[108:111], v[134:137], v[186:189], v[108:111]
	v_mfma_f32_16x16x32_bf16 v[104:107], v[142:145], v[186:189], v[104:107]
	v_mfma_f32_16x16x32_bf16 v[92:95], v[134:137], v[194:197], v[92:95]
	v_mfma_f32_16x16x32_bf16 v[88:91], v[142:145], v[194:197], v[88:91]
	v_mfma_f32_16x16x32_bf16 v[76:79], v[134:137], v[202:205], v[76:79]
	v_mfma_f32_16x16x32_bf16 v[72:75], v[142:145], v[202:205], v[72:75]
	v_mfma_f32_16x16x32_bf16 v[124:127], v[138:141], v[182:185], v[124:127]
	v_mfma_f32_16x16x32_bf16 v[120:123], v[146:149], v[182:185], v[120:123]
	v_mfma_f32_16x16x32_bf16 v[108:111], v[138:141], v[190:193], v[108:111]
	v_mfma_f32_16x16x32_bf16 v[104:107], v[146:149], v[190:193], v[104:107]
	v_mfma_f32_16x16x32_bf16 v[92:95], v[138:141], v[198:201], v[92:95]
	v_mfma_f32_16x16x32_bf16 v[88:91], v[146:149], v[198:201], v[88:91]
	v_mfma_f32_16x16x32_bf16 v[76:79], v[138:141], v[206:209], v[76:79]
	v_mfma_f32_16x16x32_bf16 v[72:75], v[146:149], v[206:209], v[72:75]
	s_setprio 0
	s_setprio 1
	v_mfma_f32_16x16x32_bf16 v[116:119], v[150:153], v[178:181], v[116:119]
	v_mfma_f32_16x16x32_bf16 v[112:115], v[170:173], v[178:181], v[112:115]
	v_mfma_f32_16x16x32_bf16 v[100:103], v[150:153], v[186:189], v[100:103]
	v_mfma_f32_16x16x32_bf16 v[96:99], v[170:173], v[186:189], v[96:99]
	v_mfma_f32_16x16x32_bf16 v[84:87], v[150:153], v[194:197], v[84:87]
	v_mfma_f32_16x16x32_bf16 v[80:83], v[170:173], v[194:197], v[80:83]
	v_mfma_f32_16x16x32_bf16 v[68:71], v[150:153], v[202:205], v[68:71]
	v_mfma_f32_16x16x32_bf16 v[64:67], v[170:173], v[202:205], v[64:67]
	v_mfma_f32_16x16x32_bf16 v[116:119], v[166:169], v[182:185], v[116:119]
	v_mfma_f32_16x16x32_bf16 v[112:115], v[174:177], v[182:185], v[112:115]
	v_mfma_f32_16x16x32_bf16 v[100:103], v[166:169], v[190:193], v[100:103]
	v_mfma_f32_16x16x32_bf16 v[96:99], v[174:177], v[190:193], v[96:99]
	v_mfma_f32_16x16x32_bf16 v[84:87], v[166:169], v[198:201], v[84:87]
	v_mfma_f32_16x16x32_bf16 v[80:83], v[174:177], v[198:201], v[80:83]
	v_mfma_f32_16x16x32_bf16 v[68:71], v[166:169], v[206:209], v[68:71]
	v_mfma_f32_16x16x32_bf16 v[64:67], v[174:177], v[206:209], v[64:67]
	s_setprio 0
	s_barrier
; #define PG8_STAGE(bufoff, gbase, voff) do { _Pragma("unroll") for (int _i = 0; _i < 2; ++_i) \
;         __builtin_amdgcn_global_load_lds((const unsigned*)((const char*)(gbase) + (voff)[_i]), (PG8_LAS unsigned*)(lds + (bufoff) + ldsw + _i * 8192), 16, 0, 0); } while (0)
; #define PG8_LDA(dst, b, h) do { _Pragma("unroll") for (int m = 0; m < 4; ++m) _Pragma("unroll") for (int k = 0; k < 2; ++k) dst[m][k] = *(const PG8_LAS bf16x8*)(lds + PG8_SA(b, h) + aoff + m * 2048 + k * 1024); } while (0)
; #define PG8_MMA(ai, bj, At, Bt) do { __builtin_amdgcn_s_setprio(1); _Pragma("unroll") for (int m = 0; m < 4; ++m) _Pragma("unroll") for (int n = 0; n < 2; ++n) _Pragma("unroll") for (int k = 0; k < 2; ++k) \
;         acc[ai][bj][m][n] = __builtin_amdgcn_mfma_f32_16x16x32_bf16(Bt[n][k], At[m][k], acc[ai][bj][m][n], 0, 0, 0); __builtin_amdgcn_s_setprio(0); } while (0)
; #define PG8_WAIT_V(n) asm volatile("s_waitcnt vmcnt(" #n ")" ::: "memory")
; #define PG8_WAIT_L(n) asm volatile("s_waitcnt lgkmcnt(" #n ")" ::: "memory")
; #define PG8_BAR __builtin_amdgcn_s_barrier()
; #define PG8_SCHED __builtin_amdgcn_sched_barrier(0)
; template <class Epi, class Sched, bool ALIGN_EPI = false, bool SP2 = false>
; __device__ __forceinline__ void gemm_phase(PG8_LAS unsigned char* lds, const Gemm g, const Sched& S, const Epi& E, int tid_in) {
;     ...
;         for (int t = 0; t < nt; t += 2) {
;             const bool last = (t == nt - 2);
;             const char* a1 = cA + (size_t)(t + 1) * kstep;
;             const char* a2 = last ? nA : cA + (size_t)(t + 2) * kstep; const char* b2 = last ? nB : cB + (size_t)(t + 2) * kstep;
;             const char* a3 = a2 + kstep; const char* b3 = b2 + kstep;
;     ...
;             PG8_LDA(At, 1, 1); PG8_STAGE(PG8_SB(1, 0), b3, voffB); PG8_STAGE(PG8_SB(1, 1), b3 + hstep, voffB); PG8_STAGE(PG8_SA(1, 0), a3, voffA);
;             PG8_WAIT_V(8); PG8_WAIT_L(0); PG8_BAR; PG8_MMA(1, 0, At, B0); PG8_MMA(1, 1, At, B1); PG8_BAR; PG8_SCHED;
	s_add_i32 s2, s37, s46
	v_lshl_add_u64 v[154:155], v[154:155], 0, s[64:65]
	s_mov_b32 m0, s2
	ds_read_b128 v[178:181], v241 offset:49152
	ds_read_b128 v[182:185], v241 offset:50176
	ds_read_b128 v[186:189], v241 offset:51200
	ds_read_b128 v[190:193], v241 offset:52224
	ds_read_b128 v[194:197], v241 offset:53248
	ds_read_b128 v[198:201], v241 offset:54272
	ds_read_b128 v[202:205], v241 offset:55296
	ds_read_b128 v[206:209], v241 offset:56320
	global_load_lds_dwordx4 v[154:155], off
	v_lshl_add_u64 v[154:155], v[162:163], 0, s[64:65]
	s_add_i32 m0, s2, 0x2000
	s_add_i32 s2, vcc_hi, s46
	global_load_lds_dwordx4 v[154:155], off
	v_lshl_add_u64 v[154:155], v[210:211], 0, s[64:65]
	s_mov_b32 m0, s2
	s_nop 0
	global_load_lds_dwordx4 v[154:155], off
	v_lshl_add_u64 v[154:155], v[212:213], 0, s[64:65]
	s_add_i32 m0, s2, 0x2000
	s_nop 0
	global_load_lds_dwordx4 v[154:155], off
	v_lshl_add_u64 v[154:155], v[214:215], 0, s[64:65]
	s_mov_b32 m0, s88
	s_nop 0
	global_load_lds_dwordx4 v[154:155], off
	v_lshl_add_u64 v[154:155], v[216:217], 0, s[64:65]
	s_mov_b32 m0, s89
	s_nop 0
	global_load_lds_dwordx4 v[154:155], off
	s_waitcnt vmcnt(8)
	s_waitcnt lgkmcnt(0)
	s_barrier
	s_setprio 1
	v_mfma_f32_16x16x32_bf16 v[60:63], v[134:137], v[178:181], v[60:63]
	v_mfma_f32_16x16x32_bf16 v[56:59], v[142:145], v[178:181], v[56:59]
	v_mfma_f32_16x16x32_bf16 v[44:47], v[134:137], v[186:189], v[44:47]
	v_mfma_f32_16x16x32_bf16 v[40:43], v[142:145], v[186:189], v[40:43]
	v_mfma_f32_16x16x32_bf16 v[28:31], v[134:137], v[194:197], v[28:31]
	v_mfma_f32_16x16x32_bf16 v[24:27], v[142:145], v[194:197], v[24:27]
	v_mfma_f32_16x16x32_bf16 v[12:15], v[134:137], v[202:205], v[12:15]
	v_mfma_f32_16x16x32_bf16 v[8:11], v[142:145], v[202:205], v[8:11]
	v_mfma_f32_16x16x32_bf16 v[60:63], v[138:141], v[182:185], v[60:63]
	v_mfma_f32_16x16x32_bf16 v[56:59], v[146:149], v[182:185], v[56:59]
	v_mfma_f32_16x16x32_bf16 v[44:47], v[138:141], v[190:193], v[44:47]
	v_mfma_f32_16x16x32_bf16 v[40:43], v[146:149], v[190:193], v[40:43]
	v_mfma_f32_16x16x32_bf16 v[28:31], v[138:141], v[198:201], v[28:31]
	v_mfma_f32_16x16x32_bf16 v[24:27], v[146:149], v[198:201], v[24:27]
	v_mfma_f32_16x16x32_bf16 v[12:15], v[138:141], v[206:209], v[12:15]
	v_mfma_f32_16x16x32_bf16 v[8:11], v[146:149], v[206:209], v[8:11]
	s_setprio 0
	s_setprio 1
	v_mfma_f32_16x16x32_bf16 v[52:55], v[150:153], v[178:181], v[52:55]
	v_mfma_f32_16x16x32_bf16 v[48:51], v[170:173], v[178:181], v[48:51]
	v_mfma_f32_16x16x32_bf16 v[36:39], v[150:153], v[186:189], v[36:39]
	v_mfma_f32_16x16x32_bf16 v[32:35], v[170:173], v[186:189], v[32:35]
	v_mfma_f32_16x16x32_bf16 v[20:23], v[150:153], v[194:197], v[20:23]
	v_mfma_f32_16x16x32_bf16 v[16:19], v[170:173], v[194:197], v[16:19]
	v_mfma_f32_16x16x32_bf16 v[4:7], v[150:153], v[202:205], v[4:7]
	v_mfma_f32_16x16x32_bf16 v[0:3], v[170:173], v[202:205], v[0:3]
	v_mfma_f32_16x16x32_bf16 v[52:55], v[166:169], v[182:185], v[52:55]
	v_mfma_f32_16x16x32_bf16 v[48:51], v[174:177], v[182:185], v[48:51]
	v_mfma_f32_16x16x32_bf16 v[36:39], v[166:169], v[190:193], v[36:39]
	v_mfma_f32_16x16x32_bf16 v[32:35], v[174:177], v[190:193], v[32:35]
	v_mfma_f32_16x16x32_bf16 v[20:23], v[166:169], v[198:201], v[20:23]
	v_mfma_f32_16x16x32_bf16 v[16:19], v[174:177], v[198:201], v[16:19]
	v_mfma_f32_16x16x32_bf16 v[4:7], v[166:169], v[206:209], v[4:7]
	v_mfma_f32_16x16x32_bf16 v[0:3], v[174:177], v[206:209], v[0:3]
	s_setprio 0
	s_barrier
	s_add_u32 s0, s0, 0x100
	s_addc_u32 s1, s1, 0
	s_add_u32 s63, s63, 0x100
	s_addc_u32 vcc_lo, vcc_lo, 0
	s_cmp_ge_i32 s36, s67
	s_mov_b32 s22, s36
	s_cbranch_scc0 .LBB0_820

; #define PG8_STAGE(bufoff, gbase, voff) do { _Pragma("unroll") for (int _i = 0; _i < 2; ++_i) \
;         __builtin_amdgcn_global_load_lds((const unsigned*)((const char*)(gbase) + (voff)[_i]), (PG8_LAS unsigned*)(lds + (bufoff) + ldsw + _i * 8192), 16, 0, 0); } while (0)
; #define PG8_LDA(dst, b, h) do { _Pragma("unroll") for (int m = 0; m < 4; ++m) _Pragma("unroll") for (int k = 0; k < 2; ++k) dst[m][k] = *(const PG8_LAS bf16x8*)(lds + PG8_SA(b, h) + aoff + m * 2048 + k * 1024); } while (0)
; #define PG8_LDB(dst, b, h) do { _Pragma("unroll") for (int n = 0; n < 2; ++n) _Pragma("unroll") for (int k = 0; k < 2; ++k) dst[n][k] = *(const PG8_LAS bf16x8*)(lds + PG8_SB(b, h) + boff + n * 2048 + k * 1024); } while (0)
; #define PG8_MMA(ai, bj, At, Bt) do { __builtin_amdgcn_s_setprio(1); _Pragma("unroll") for (int m = 0; m < 4; ++m) _Pragma("unroll") for (int n = 0; n < 2; ++n) _Pragma("unroll") for (int k = 0; k < 2; ++k) \
;         acc[ai][bj][m][n] = __builtin_amdgcn_mfma_f32_16x16x32_bf16(Bt[n][k], At[m][k], acc[ai][bj][m][n], 0, 0, 0); __builtin_amdgcn_s_setprio(0); } while (0)
; #define PG8_WAIT_V(n) asm volatile("s_waitcnt vmcnt(" #n ")" ::: "memory")
; #define PG8_WAIT_L(n) asm volatile("s_waitcnt lgkmcnt(" #n ")" ::: "memory")
; #define PG8_BAR __builtin_amdgcn_s_barrier()
; #define PG8_SCHED __builtin_amdgcn_sched_barrier(0)
; template <class Epi, class Sched, bool ALIGN_EPI = false, bool SP2 = false>
; __device__ __forceinline__ void gemm_phase(PG8_LAS unsigned char* lds, const Gemm g, const Sched& S, const Epi& E, int tid_in) {
;     ...
;             PG8_LDB(B0, 0, 0); PG8_LDB(B1, 0, 1); PG8_SCHED; PG8_LDA(At, 0, 0); PG8_STAGE(PG8_SA(1, 1), a1 + hstep, voffA);
;             PG8_WAIT_V(8); PG8_WAIT_L(0); PG8_BAR; PG8_MMA(0, 0, At, B0); PG8_MMA(0, 1, At, B1); PG8_BAR; PG8_SCHED;
;             PG8_LDA(At, 0, 1); PG8_STAGE(PG8_SB(0, 0), b2, voffB); PG8_STAGE(PG8_SB(0, 1), b2 + hstep, voffB); PG8_STAGE(PG8_SA(0, 0), a2, voffA);
;             PG8_WAIT_V(8); PG8_WAIT_L(0); PG8_BAR; PG8_MMA(1, 0, At, B0); PG8_MMA(1, 1, At, B1); PG8_BAR; PG8_SCHED;
.LBB0_928:
	s_add_i32 s36, s6, 2
	s_add_u32 s2, s0, 0x80
	s_addc_u32 s3, s1, 0
	s_add_i32 s37, 0, 0x10000
	s_cmp_eq_u32 s60, s6
	s_cselect_b32 s7, s63, s3
	s_cselect_b32 s6, s62, s2
	v_add_u32_e32 v144, s37, v151
	s_cselect_b32 s3, s67, s23
	s_cselect_b32 s2, s66, s22
	s_add_i32 s91, 0, 0x14000
	ds_read_b128 v[140:143], v144
	ds_read_b128 v[168:171], v144 offset:1024
	ds_read_b128 v[172:175], v144 offset:2048
	ds_read_b128 v[176:179], v144 offset:3072
	v_add_u32_e32 v144, s91, v151
	ds_read_b128 v[180:183], v144
	ds_read_b128 v[184:187], v144 offset:1024
	ds_read_b128 v[188:191], v144 offset:2048
	ds_read_b128 v[192:195], v144 offset:3072
	v_lshl_add_u64 v[146:147], s[0:1], 0, v[136:137]
	s_add_i32 m0, s43, 0xc000
	ds_read_b128 v[196:199], v167
	ds_read_b128 v[200:203], v167 offset:1024
	ds_read_b128 v[204:207], v167 offset:2048
	ds_read_b128 v[208:211], v167 offset:3072
	ds_read_b128 v[212:215], v167 offset:4096
	ds_read_b128 v[216:219], v167 offset:5120
	ds_read_b128 v[220:223], v167 offset:6144
	ds_read_b128 v[224:227], v167 offset:7168
	global_load_lds_dwordx4 v[146:147], off
	v_lshl_add_u64 v[146:147], s[0:1], 0, v[138:139]
	s_add_i32 m0, s43, 0xe000
	s_nop 0
	global_load_lds_dwordx4 v[146:147], off
	s_waitcnt vmcnt(8)
	s_waitcnt lgkmcnt(0)
	s_barrier
	s_setprio 1
	v_mfma_f32_16x16x32_bf16 v[124:127], v[140:143], v[196:199], v[124:127]
	v_mfma_f32_16x16x32_bf16 v[120:123], v[172:175], v[196:199], v[120:123]
	v_mfma_f32_16x16x32_bf16 v[108:111], v[140:143], v[204:207], v[108:111]
	v_mfma_f32_16x16x32_bf16 v[104:107], v[172:175], v[204:207], v[104:107]
	v_mfma_f32_16x16x32_bf16 v[92:95], v[140:143], v[212:215], v[92:95]
	v_mfma_f32_16x16x32_bf16 v[88:91], v[172:175], v[212:215], v[88:91]
	v_mfma_f32_16x16x32_bf16 v[76:79], v[140:143], v[220:223], v[76:79]
	v_mfma_f32_16x16x32_bf16 v[72:75], v[172:175], v[220:223], v[72:75]
	v_mfma_f32_16x16x32_bf16 v[124:127], v[168:171], v[200:203], v[124:127]
	v_mfma_f32_16x16x32_bf16 v[120:123], v[176:179], v[200:203], v[120:123]
	v_mfma_f32_16x16x32_bf16 v[108:111], v[168:171], v[208:211], v[108:111]
	v_mfma_f32_16x16x32_bf16 v[104:107], v[176:179], v[208:211], v[104:107]
	v_mfma_f32_16x16x32_bf16 v[92:95], v[168:171], v[216:219], v[92:95]
	v_mfma_f32_16x16x32_bf16 v[88:91], v[176:179], v[216:219], v[88:91]
	v_mfma_f32_16x16x32_bf16 v[76:79], v[168:171], v[224:227], v[76:79]
	v_mfma_f32_16x16x32_bf16 v[72:75], v[176:179], v[224:227], v[72:75]
	s_setprio 0
	s_setprio 1
	v_mfma_f32_16x16x32_bf16 v[116:119], v[180:183], v[196:199], v[116:119]
	v_mfma_f32_16x16x32_bf16 v[112:115], v[188:191], v[196:199], v[112:115]
	v_mfma_f32_16x16x32_bf16 v[100:103], v[180:183], v[204:207], v[100:103]
	v_mfma_f32_16x16x32_bf16 v[96:99], v[188:191], v[204:207], v[96:99]
	v_mfma_f32_16x16x32_bf16 v[84:87], v[180:183], v[212:215], v[84:87]
	v_mfma_f32_16x16x32_bf16 v[80:83], v[188:191], v[212:215], v[80:83]
	v_mfma_f32_16x16x32_bf16 v[68:71], v[180:183], v[220:223], v[68:71]
	v_mfma_f32_16x16x32_bf16 v[64:67], v[188:191], v[220:223], v[64:67]
	v_mfma_f32_16x16x32_bf16 v[116:119], v[184:187], v[200:203], v[116:119]
	v_mfma_f32_16x16x32_bf16 v[112:115], v[192:195], v[200:203], v[112:115]
	v_mfma_f32_16x16x32_bf16 v[100:103], v[184:187], v[208:211], v[100:103]
	v_mfma_f32_16x16x32_bf16 v[96:99], v[192:195], v[208:211], v[96:99]
	v_mfma_f32_16x16x32_bf16 v[84:87], v[184:187], v[216:219], v[84:87]
	v_mfma_f32_16x16x32_bf16 v[80:83], v[192:195], v[216:219], v[80:83]
	v_mfma_f32_16x16x32_bf16 v[68:71], v[184:187], v[224:227], v[68:71]
	v_mfma_f32_16x16x32_bf16 v[64:67], v[192:195], v[224:227], v[64:67]
	s_setprio 0
	s_barrier
	s_add_i32 s37, s37, s42
	v_lshl_add_u64 v[146:147], s[2:3], 0, v[156:157]
	s_mov_b32 m0, s37
	ds_read_b128 v[196:199], v167 offset:16384
	ds_read_b128 v[200:203], v167 offset:17408
	ds_read_b128 v[204:207], v167 offset:18432
	ds_read_b128 v[208:211], v167 offset:19456
	ds_read_b128 v[212:215], v167 offset:20480
	ds_read_b128 v[216:219], v167 offset:21504
	ds_read_b128 v[220:223], v167 offset:22528
	ds_read_b128 v[224:227], v167 offset:23552
	global_load_lds_dwordx4 v[146:147], off
	s_add_i32 m0, s37, 0x2000
	v_lshl_add_u64 v[162:163], s[2:3], 0, v[128:129]
	s_add_u32 s2, s2, s10
	s_addc_u32 s3, s3, s11
	s_add_i32 s37, s91, s42
	global_load_lds_dwordx4 v[162:163], off
	v_lshl_add_u64 v[228:229], s[2:3], 0, v[156:157]
	s_mov_b32 m0, s37
	v_lshl_add_u64 v[230:231], s[2:3], 0, v[128:129]
	global_load_lds_dwordx4 v[228:229], off
	s_add_i32 m0, s37, 0x2000
	v_lshl_add_u64 v[238:239], s[6:7], 0, v[132:133]
	global_load_lds_dwordx4 v[230:231], off
	s_mov_b32 m0, s43
	v_lshl_add_u64 v[240:241], s[6:7], 0, v[130:131]
	global_load_lds_dwordx4 v[238:239], off
	s_mov_b32 m0, s44
	s_nop 0
	global_load_lds_dwordx4 v[240:241], off
	s_waitcnt vmcnt(8)
	s_waitcnt lgkmcnt(0)
	s_barrier
; #define PG8_STAGE(bufoff, gbase, voff) do { _Pragma("unroll") for (int _i = 0; _i < 2; ++_i) \
;         __builtin_amdgcn_global_load_lds((const unsigned*)((const char*)(gbase) + (voff)[_i]), (PG8_LAS unsigned*)(lds + (bufoff) + ldsw + _i * 8192), 16, 0, 0); } while (0)
; #define PG8_LDA(dst, b, h) do { _Pragma("unroll") for (int m = 0; m < 4; ++m) _Pragma("unroll") for (int k = 0; k < 2; ++k) dst[m][k] = *(const PG8_LAS bf16x8*)(lds + PG8_SA(b, h) + aoff + m * 2048 + k * 1024); } while (0)
; #define PG8_LDB(dst, b, h) do { _Pragma("unroll") for (int n = 0; n < 2; ++n) _Pragma("unroll") for (int k = 0; k < 2; ++k) dst[n][k] = *(const PG8_LAS bf16x8*)(lds + PG8_SB(b, h) + boff + n * 2048 + k * 1024); } while (0)
; #define PG8_MMA(ai, bj, At, Bt) do { __builtin_amdgcn_s_setprio(1); _Pragma("unroll") for (int m = 0; m < 4; ++m) _Pragma("unroll") for (int n = 0; n < 2; ++n) _Pragma("unroll") for (int k = 0; k < 2; ++k) \
;         acc[ai][bj][m][n] = __builtin_amdgcn_mfma_f32_16x16x32_bf16(Bt[n][k], At[m][k], acc[ai][bj][m][n], 0, 0, 0); __builtin_amdgcn_s_setprio(0); } while (0)
; #define PG8_WAIT_V(n) asm volatile("s_waitcnt vmcnt(" #n ")" ::: "memory")
; #define PG8_WAIT_L(n) asm volatile("s_waitcnt lgkmcnt(" #n ")" ::: "memory")
; #define PG8_BAR __builtin_amdgcn_s_barrier()
; #define PG8_SCHED __builtin_amdgcn_sched_barrier(0)
; template <class Epi, class Sched, bool ALIGN_EPI = false, bool SP2 = false>
; __device__ __forceinline__ void gemm_phase(PG8_LAS unsigned char* lds, const Gemm g, const Sched& S, const Epi& E, int tid_in) {
;     ...
;             PG8_WAIT_V(8); PG8_WAIT_L(0); PG8_BAR; PG8_MMA(1, 0, At, B0); PG8_MMA(1, 1, At, B1); PG8_BAR; PG8_SCHED;
;             PG8_LDB(B0, 1, 0); PG8_LDB(B1, 1, 1); PG8_SCHED; PG8_LDA(At, 1, 0); PG8_STAGE(PG8_SA(0, 1), a2 + hstep, voffA);
;             PG8_WAIT_V(8); PG8_WAIT_L(0); PG8_BAR; PG8_MMA(0, 0, At, B0); PG8_MMA(0, 1, At, B1); PG8_BAR; PG8_SCHED;
	s_setprio 1
	v_mfma_f32_16x16x32_bf16 v[60:63], v[140:143], v[196:199], v[60:63]
	v_mfma_f32_16x16x32_bf16 v[56:59], v[172:175], v[196:199], v[56:59]
	v_mfma_f32_16x16x32_bf16 v[44:47], v[140:143], v[204:207], v[44:47]
	v_mfma_f32_16x16x32_bf16 v[40:43], v[172:175], v[204:207], v[40:43]
	v_mfma_f32_16x16x32_bf16 v[28:31], v[140:143], v[212:215], v[28:31]
	v_mfma_f32_16x16x32_bf16 v[24:27], v[172:175], v[212:215], v[24:27]
	v_mfma_f32_16x16x32_bf16 v[12:15], v[140:143], v[220:223], v[12:15]
	v_mfma_f32_16x16x32_bf16 v[8:11], v[172:175], v[220:223], v[8:11]
	v_mfma_f32_16x16x32_bf16 v[60:63], v[168:171], v[200:203], v[60:63]
	v_mfma_f32_16x16x32_bf16 v[56:59], v[176:179], v[200:203], v[56:59]
	v_mfma_f32_16x16x32_bf16 v[44:47], v[168:171], v[208:211], v[44:47]
	v_mfma_f32_16x16x32_bf16 v[40:43], v[176:179], v[208:211], v[40:43]
	v_mfma_f32_16x16x32_bf16 v[28:31], v[168:171], v[216:219], v[28:31]
	v_mfma_f32_16x16x32_bf16 v[24:27], v[176:179], v[216:219], v[24:27]
	v_mfma_f32_16x16x32_bf16 v[12:15], v[168:171], v[224:227], v[12:15]
	v_mfma_f32_16x16x32_bf16 v[8:11], v[176:179], v[224:227], v[8:11]
	s_setprio 0
	s_setprio 1
	v_mfma_f32_16x16x32_bf16 v[52:55], v[180:183], v[196:199], v[52:55]
	v_mfma_f32_16x16x32_bf16 v[48:51], v[188:191], v[196:199], v[48:51]
	v_mfma_f32_16x16x32_bf16 v[36:39], v[180:183], v[204:207], v[36:39]
	v_mfma_f32_16x16x32_bf16 v[32:35], v[188:191], v[204:207], v[32:35]
	v_mfma_f32_16x16x32_bf16 v[20:23], v[180:183], v[212:215], v[20:23]
	v_mfma_f32_16x16x32_bf16 v[16:19], v[188:191], v[212:215], v[16:19]
	v_mfma_f32_16x16x32_bf16 v[4:7], v[180:183], v[220:223], v[4:7]
	v_mfma_f32_16x16x32_bf16 v[0:3], v[188:191], v[220:223], v[0:3]
	v_mfma_f32_16x16x32_bf16 v[52:55], v[184:187], v[200:203], v[52:55]
	v_mfma_f32_16x16x32_bf16 v[48:51], v[192:195], v[200:203], v[48:51]
	v_mfma_f32_16x16x32_bf16 v[36:39], v[184:187], v[208:211], v[36:39]
	v_mfma_f32_16x16x32_bf16 v[32:35], v[192:195], v[208:211], v[32:35]
	v_mfma_f32_16x16x32_bf16 v[20:23], v[184:187], v[216:219], v[20:23]
	v_mfma_f32_16x16x32_bf16 v[16:19], v[192:195], v[216:219], v[16:19]
	v_mfma_f32_16x16x32_bf16 v[4:7], v[184:187], v[224:227], v[4:7]
	v_mfma_f32_16x16x32_bf16 v[0:3], v[192:195], v[224:227], v[0:3]
	s_setprio 0
	s_barrier
	s_add_i32 s37, 0, 0x18000
	v_add_u32_e32 v144, s37, v151
	s_add_i32 s91, 0, 0x1c000
	ds_read_b128 v[140:143], v144
	ds_read_b128 v[168:171], v144 offset:1024
	ds_read_b128 v[172:175], v144 offset:2048
	ds_read_b128 v[176:179], v144 offset:3072
	v_add_u32_e32 v144, s91, v151
	ds_read_b128 v[180:183], v144
	ds_read_b128 v[184:187], v144 offset:1024
	ds_read_b128 v[188:191], v144 offset:2048
	ds_read_b128 v[192:195], v144 offset:3072
	s_add_u32 s2, s6, s10
	s_addc_u32 s3, s7, s11
	s_mov_b32 m0, s45
	v_lshl_add_u64 v[242:243], s[2:3], 0, v[132:133]
	ds_read_b128 v[196:199], v167 offset:32768
	ds_read_b128 v[200:203], v167 offset:33792
	ds_read_b128 v[204:207], v167 offset:34816
	ds_read_b128 v[208:211], v167 offset:35840
	ds_read_b128 v[212:215], v167 offset:36864
	ds_read_b128 v[216:219], v167 offset:37888
	ds_read_b128 v[220:223], v167 offset:38912
	ds_read_b128 v[224:227], v167 offset:39936
	global_load_lds_dwordx4 v[242:243], off
	v_lshl_add_u64 v[242:243], s[2:3], 0, v[130:131]
	s_mov_b32 m0, s46
	s_nop 0
	global_load_lds_dwordx4 v[242:243], off
	s_waitcnt vmcnt(8)
	s_waitcnt lgkmcnt(0)
	s_barrier
	s_setprio 1
	v_mfma_f32_16x16x32_bf16 v[124:127], v[140:143], v[196:199], v[124:127]
	v_mfma_f32_16x16x32_bf16 v[120:123], v[172:175], v[196:199], v[120:123]
	v_mfma_f32_16x16x32_bf16 v[108:111], v[140:143], v[204:207], v[108:111]
	v_mfma_f32_16x16x32_bf16 v[104:107], v[172:175], v[204:207], v[104:107]
	v_mfma_f32_16x16x32_bf16 v[92:95], v[140:143], v[212:215], v[92:95]
	v_mfma_f32_16x16x32_bf16 v[88:91], v[172:175], v[212:215], v[88:91]
	v_mfma_f32_16x16x32_bf16 v[76:79], v[140:143], v[220:223], v[76:79]
	v_mfma_f32_16x16x32_bf16 v[72:75], v[172:175], v[220:223], v[72:75]
	v_mfma_f32_16x16x32_bf16 v[124:127], v[168:171], v[200:203], v[124:127]
	v_mfma_f32_16x16x32_bf16 v[120:123], v[176:179], v[200:203], v[120:123]
	v_mfma_f32_16x16x32_bf16 v[108:111], v[168:171], v[208:211], v[108:111]
	v_mfma_f32_16x16x32_bf16 v[104:107], v[176:179], v[208:211], v[104:107]
	v_mfma_f32_16x16x32_bf16 v[92:95], v[168:171], v[216:219], v[92:95]
	v_mfma_f32_16x16x32_bf16 v[88:91], v[176:179], v[216:219], v[88:91]
	v_mfma_f32_16x16x32_bf16 v[76:79], v[168:171], v[224:227], v[76:79]
	v_mfma_f32_16x16x32_bf16 v[72:75], v[176:179], v[224:227], v[72:75]
	s_setprio 0
	s_setprio 1
	v_mfma_f32_16x16x32_bf16 v[116:119], v[180:183], v[196:199], v[116:119]
	v_mfma_f32_16x16x32_bf16 v[112:115], v[188:191], v[196:199], v[112:115]
	v_mfma_f32_16x16x32_bf16 v[100:103], v[180:183], v[204:207], v[100:103]
	v_mfma_f32_16x16x32_bf16 v[96:99], v[188:191], v[204:207], v[96:99]
	v_mfma_f32_16x16x32_bf16 v[84:87], v[180:183], v[212:215], v[84:87]
	v_mfma_f32_16x16x32_bf16 v[80:83], v[188:191], v[212:215], v[80:83]
	v_mfma_f32_16x16x32_bf16 v[68:71], v[180:183], v[220:223], v[68:71]
	v_mfma_f32_16x16x32_bf16 v[64:67], v[188:191], v[220:223], v[64:67]
	v_mfma_f32_16x16x32_bf16 v[116:119], v[184:187], v[200:203], v[116:119]
	v_mfma_f32_16x16x32_bf16 v[112:115], v[192:195], v[200:203], v[112:115]
	v_mfma_f32_16x16x32_bf16 v[100:103], v[184:187], v[208:211], v[100:103]
	v_mfma_f32_16x16x32_bf16 v[96:99], v[192:195], v[208:211], v[96:99]
	v_mfma_f32_16x16x32_bf16 v[84:87], v[184:187], v[216:219], v[84:87]
	v_mfma_f32_16x16x32_bf16 v[80:83], v[192:195], v[216:219], v[80:83]
	v_mfma_f32_16x16x32_bf16 v[68:71], v[184:187], v[224:227], v[68:71]
	v_mfma_f32_16x16x32_bf16 v[64:67], v[192:195], v[224:227], v[64:67]
	s_setprio 0
	s_barrier
; #define PG8_STAGE(bufoff, gbase, voff) do { _Pragma("unroll") for (int _i = 0; _i < 2; ++_i) \
;         __builtin_amdgcn_global_load_lds((const unsigned*)((const char*)(gbase) + (voff)[_i]), (PG8_LAS unsigned*)(lds + (bufoff) + ldsw + _i * 8192), 16, 0, 0); } while (0)
; #define PG8_LDA(dst, b, h) do { _Pragma("unroll") for (int m = 0; m < 4; ++m) _Pragma("unroll") for (int k = 0; k < 2; ++k) dst[m][k] = *(const PG8_LAS bf16x8*)(lds + PG8_SA(b, h) + aoff + m * 2048 + k * 1024); } while (0)
; #define PG8_MMA(ai, bj, At, Bt) do { __builtin_amdgcn_s_setprio(1); _Pragma("unroll") for (int m = 0; m < 4; ++m) _Pragma("unroll") for (int n = 0; n < 2; ++n) _Pragma("unroll") for (int k = 0; k < 2; ++k) \
;         acc[ai][bj][m][n] = __builtin_amdgcn_mfma_f32_16x16x32_bf16(Bt[n][k], At[m][k], acc[ai][bj][m][n], 0, 0, 0); __builtin_amdgcn_s_setprio(0); } while (0)
; #define PG8_WAIT_V(n) asm volatile("s_waitcnt vmcnt(" #n ")" ::: "memory")
; #define PG8_WAIT_L(n) asm volatile("s_waitcnt lgkmcnt(" #n ")" ::: "memory")
; #define PG8_BAR __builtin_amdgcn_s_barrier()
; #define PG8_SCHED __builtin_amdgcn_sched_barrier(0)
; template <class Epi, class Sched, bool ALIGN_EPI = false, bool SP2 = false>
; __device__ __forceinline__ void gemm_phase(PG8_LAS unsigned char* lds, const Gemm g, const Sched& S, const Epi& E, int tid_in) {
;     ...
;         for (int t = 0; t < nt; t += 2) {
;             const bool last = (t == nt - 2);
;             const char* a1 = cA + (size_t)(t + 1) * kstep;
;             const char* a2 = last ? nA : cA + (size_t)(t + 2) * kstep; const char* b2 = last ? nB : cB + (size_t)(t + 2) * kstep;
;             const char* a3 = a2 + kstep; const char* b3 = b2 + kstep;
;     ...
;             PG8_LDA(At, 1, 1); PG8_STAGE(PG8_SB(1, 0), b3, voffB); PG8_STAGE(PG8_SB(1, 1), b3 + hstep, voffB); PG8_STAGE(PG8_SA(1, 0), a3, voffA);
;             PG8_WAIT_V(8); PG8_WAIT_L(0); PG8_BAR; PG8_MMA(1, 0, At, B0); PG8_MMA(1, 1, At, B1); PG8_BAR; PG8_SCHED;
	s_add_i32 s2, s37, s42
	v_lshl_add_u64 v[146:147], v[146:147], 0, s[64:65]
	s_mov_b32 m0, s2
	ds_read_b128 v[196:199], v167 offset:49152
	ds_read_b128 v[200:203], v167 offset:50176
	ds_read_b128 v[204:207], v167 offset:51200
	ds_read_b128 v[208:211], v167 offset:52224
	ds_read_b128 v[212:215], v167 offset:53248
	ds_read_b128 v[216:219], v167 offset:54272
	ds_read_b128 v[220:223], v167 offset:55296
	ds_read_b128 v[224:227], v167 offset:56320
	global_load_lds_dwordx4 v[146:147], off
	v_lshl_add_u64 v[146:147], v[162:163], 0, s[64:65]
	s_add_i32 m0, s2, 0x2000
	s_add_i32 s2, s91, s42
	global_load_lds_dwordx4 v[146:147], off
	v_lshl_add_u64 v[146:147], v[228:229], 0, s[64:65]
	s_mov_b32 m0, s2
	s_nop 0
	global_load_lds_dwordx4 v[146:147], off
	v_lshl_add_u64 v[146:147], v[230:231], 0, s[64:65]
	s_add_i32 m0, s2, 0x2000
	s_nop 0
	global_load_lds_dwordx4 v[146:147], off
	v_lshl_add_u64 v[146:147], v[238:239], 0, s[64:65]
	s_mov_b32 m0, s56
	s_nop 0
	global_load_lds_dwordx4 v[146:147], off
	v_lshl_add_u64 v[146:147], v[240:241], 0, s[64:65]
	s_mov_b32 m0, s57
	s_nop 0
	global_load_lds_dwordx4 v[146:147], off
	s_waitcnt vmcnt(8)
	s_waitcnt lgkmcnt(0)
	s_barrier
	s_setprio 1
	v_mfma_f32_16x16x32_bf16 v[60:63], v[140:143], v[196:199], v[60:63]
	v_mfma_f32_16x16x32_bf16 v[56:59], v[172:175], v[196:199], v[56:59]
	v_mfma_f32_16x16x32_bf16 v[44:47], v[140:143], v[204:207], v[44:47]
	v_mfma_f32_16x16x32_bf16 v[40:43], v[172:175], v[204:207], v[40:43]
	v_mfma_f32_16x16x32_bf16 v[28:31], v[140:143], v[212:215], v[28:31]
	v_mfma_f32_16x16x32_bf16 v[24:27], v[172:175], v[212:215], v[24:27]
	v_mfma_f32_16x16x32_bf16 v[12:15], v[140:143], v[220:223], v[12:15]
	v_mfma_f32_16x16x32_bf16 v[8:11], v[172:175], v[220:223], v[8:11]
	v_mfma_f32_16x16x32_bf16 v[60:63], v[168:171], v[200:203], v[60:63]
	v_mfma_f32_16x16x32_bf16 v[56:59], v[176:179], v[200:203], v[56:59]
	v_mfma_f32_16x16x32_bf16 v[44:47], v[168:171], v[208:211], v[44:47]
	v_mfma_f32_16x16x32_bf16 v[40:43], v[176:179], v[208:211], v[40:43]
	v_mfma_f32_16x16x32_bf16 v[28:31], v[168:171], v[216:219], v[28:31]
	v_mfma_f32_16x16x32_bf16 v[24:27], v[176:179], v[216:219], v[24:27]
	v_mfma_f32_16x16x32_bf16 v[12:15], v[168:171], v[224:227], v[12:15]
	v_mfma_f32_16x16x32_bf16 v[8:11], v[176:179], v[224:227], v[8:11]
	s_setprio 0
	s_setprio 1
	v_mfma_f32_16x16x32_bf16 v[52:55], v[180:183], v[196:199], v[52:55]
	v_mfma_f32_16x16x32_bf16 v[48:51], v[188:191], v[196:199], v[48:51]
	v_mfma_f32_16x16x32_bf16 v[36:39], v[180:183], v[204:207], v[36:39]
	v_mfma_f32_16x16x32_bf16 v[32:35], v[188:191], v[204:207], v[32:35]
	v_mfma_f32_16x16x32_bf16 v[20:23], v[180:183], v[212:215], v[20:23]
	v_mfma_f32_16x16x32_bf16 v[16:19], v[188:191], v[212:215], v[16:19]
	v_mfma_f32_16x16x32_bf16 v[4:7], v[180:183], v[220:223], v[4:7]
	v_mfma_f32_16x16x32_bf16 v[0:3], v[188:191], v[220:223], v[0:3]
	v_mfma_f32_16x16x32_bf16 v[52:55], v[184:187], v[200:203], v[52:55]
	v_mfma_f32_16x16x32_bf16 v[48:51], v[192:195], v[200:203], v[48:51]
	v_mfma_f32_16x16x32_bf16 v[36:39], v[184:187], v[208:211], v[36:39]
	v_mfma_f32_16x16x32_bf16 v[32:35], v[192:195], v[208:211], v[32:35]
	v_mfma_f32_16x16x32_bf16 v[20:23], v[184:187], v[216:219], v[20:23]
	v_mfma_f32_16x16x32_bf16 v[16:19], v[192:195], v[216:219], v[16:19]
	v_mfma_f32_16x16x32_bf16 v[4:7], v[184:187], v[224:227], v[4:7]
	v_mfma_f32_16x16x32_bf16 v[0:3], v[192:195], v[224:227], v[0:3]
	s_setprio 0
	s_barrier
	s_add_u32 s0, s0, 0x100
	s_addc_u32 s1, s1, 0
	s_add_u32 s22, s22, 0x100
	s_addc_u32 s23, s23, 0
	s_cmp_ge_i32 s36, s52
	s_mov_b32 s6, s36
	s_cbranch_scc0 .LBB0_928

; #define PG8_STAGE(bufoff, gbase, voff) do { _Pragma("unroll") for (int _i = 0; _i < 2; ++_i) \
;         __builtin_amdgcn_global_load_lds((const unsigned*)((const char*)(gbase) + (voff)[_i]), (PG8_LAS unsigned*)(lds + (bufoff) + ldsw + _i * 8192), 16, 0, 0); } while (0)
; #define PG8_LDA(dst, b, h) do { _Pragma("unroll") for (int m = 0; m < 4; ++m) _Pragma("unroll") for (int k = 0; k < 2; ++k) dst[m][k] = *(const PG8_LAS bf16x8*)(lds + PG8_SA(b, h) + aoff + m * 2048 + k * 1024); } while (0)
; #define PG8_LDB(dst, b, h) do { _Pragma("unroll") for (int n = 0; n < 2; ++n) _Pragma("unroll") for (int k = 0; k < 2; ++k) dst[n][k] = *(const PG8_LAS bf16x8*)(lds + PG8_SB(b, h) + boff + n * 2048 + k * 1024); } while (0)
; #define PG8_MMA(ai, bj, At, Bt) do { __builtin_amdgcn_s_setprio(1); _Pragma("unroll") for (int m = 0; m < 4; ++m) _Pragma("unroll") for (int n = 0; n < 2; ++n) _Pragma("unroll") for (int k = 0; k < 2; ++k) \
;         acc[ai][bj][m][n] = __builtin_amdgcn_mfma_f32_16x16x32_bf16(Bt[n][k], At[m][k], acc[ai][bj][m][n], 0, 0, 0); __builtin_amdgcn_s_setprio(0); } while (0)
; #define PG8_WAIT_V(n) asm volatile("s_waitcnt vmcnt(" #n ")" ::: "memory")
; #define PG8_WAIT_L(n) asm volatile("s_waitcnt lgkmcnt(" #n ")" ::: "memory")
; #define PG8_BAR __builtin_amdgcn_s_barrier()
; #define PG8_SCHED __builtin_amdgcn_sched_barrier(0)
; template <class Epi, class Sched, bool ALIGN_EPI = false, bool SP2 = false>
; __device__ __forceinline__ void gemm_phase(PG8_LAS unsigned char* lds, const Gemm g, const Sched& S, const Epi& E, int tid_in) {
;     ...
;             PG8_LDB(B0, 0, 0); PG8_LDB(B1, 0, 1); PG8_SCHED; PG8_LDA(At, 0, 0); PG8_STAGE(PG8_SA(1, 1), a1 + hstep, voffA);
;             PG8_WAIT_V(8); PG8_WAIT_L(0); PG8_BAR; PG8_MMA(0, 0, At, B0); PG8_MMA(0, 1, At, B1); PG8_BAR; PG8_SCHED;
;             PG8_LDA(At, 0, 1); PG8_STAGE(PG8_SB(0, 0), b2, voffB); PG8_STAGE(PG8_SB(0, 1), b2 + hstep, voffB); PG8_STAGE(PG8_SA(0, 0), a2, voffA);
;             PG8_WAIT_V(8); PG8_WAIT_L(0); PG8_BAR; PG8_MMA(1, 0, At, B0); PG8_MMA(1, 1, At, B1); PG8_BAR; PG8_SCHED;
.LBB0_1024:
	s_add_i32 s36, s22, 2
	s_add_u32 s37, s0, 0x80
	s_addc_u32 s23, s1, 0
	s_add_i32 s93, 0, 0x10000
	s_cmp_eq_u32 s88, s22
	s_cselect_b32 s23, s7, s23
	s_cselect_b32 s22, s6, s37
	s_cselect_b32 vcc_hi, s45, s92
	s_cselect_b32 vcc_lo, s44, s55
	s_add_i32 s37, 0, 0x14000
	v_add_u32_e32 v146, s93, v237
	v_add_u32_e32 v154, s37, v237
	ds_read_b128 v[134:137], v146
	ds_read_b128 v[138:141], v146 offset:1024
	ds_read_b128 v[142:145], v146 offset:2048
	ds_read_b128 v[146:149], v146 offset:3072
	ds_read_b128 v[150:153], v154
	ds_read_b128 v[166:169], v154 offset:1024
	ds_read_b128 v[170:173], v154 offset:2048
	ds_read_b128 v[174:177], v154 offset:3072
	v_lshl_add_u64 v[154:155], s[0:1], 0, v[130:131]
	s_add_i32 m0, s47, 0xc000
	ds_read_b128 v[178:181], v241
	ds_read_b128 v[182:185], v241 offset:1024
	ds_read_b128 v[186:189], v241 offset:2048
	ds_read_b128 v[190:193], v241 offset:3072
	ds_read_b128 v[194:197], v241 offset:4096
	ds_read_b128 v[198:201], v241 offset:5120
	ds_read_b128 v[202:205], v241 offset:6144
	ds_read_b128 v[206:209], v241 offset:7168
	global_load_lds_dwordx4 v[154:155], off
	v_lshl_add_u64 v[154:155], s[0:1], 0, v[132:133]
	s_add_i32 m0, s47, 0xe000
	s_nop 0
	global_load_lds_dwordx4 v[154:155], off
	s_waitcnt vmcnt(8)
	s_waitcnt lgkmcnt(0)
	s_barrier
	s_setprio 1
	v_mfma_f32_16x16x32_bf16 v[124:127], v[134:137], v[178:181], v[124:127]
	v_mfma_f32_16x16x32_bf16 v[120:123], v[142:145], v[178:181], v[120:123]
	v_mfma_f32_16x16x32_bf16 v[108:111], v[134:137], v[186:189], v[108:111]
	v_mfma_f32_16x16x32_bf16 v[104:107], v[142:145], v[186:189], v[104:107]
	v_mfma_f32_16x16x32_bf16 v[92:95], v[134:137], v[194:197], v[92:95]
	v_mfma_f32_16x16x32_bf16 v[88:91], v[142:145], v[194:197], v[88:91]
	v_mfma_f32_16x16x32_bf16 v[76:79], v[134:137], v[202:205], v[76:79]
	v_mfma_f32_16x16x32_bf16 v[72:75], v[142:145], v[202:205], v[72:75]
	v_mfma_f32_16x16x32_bf16 v[124:127], v[138:141], v[182:185], v[124:127]
	v_mfma_f32_16x16x32_bf16 v[120:123], v[146:149], v[182:185], v[120:123]
	v_mfma_f32_16x16x32_bf16 v[108:111], v[138:141], v[190:193], v[108:111]
	v_mfma_f32_16x16x32_bf16 v[104:107], v[146:149], v[190:193], v[104:107]
	v_mfma_f32_16x16x32_bf16 v[92:95], v[138:141], v[198:201], v[92:95]
	v_mfma_f32_16x16x32_bf16 v[88:91], v[146:149], v[198:201], v[88:91]
	v_mfma_f32_16x16x32_bf16 v[76:79], v[138:141], v[206:209], v[76:79]
	v_mfma_f32_16x16x32_bf16 v[72:75], v[146:149], v[206:209], v[72:75]
	s_setprio 0
	s_setprio 1
	v_mfma_f32_16x16x32_bf16 v[116:119], v[150:153], v[178:181], v[116:119]
	v_mfma_f32_16x16x32_bf16 v[112:115], v[170:173], v[178:181], v[112:115]
	v_mfma_f32_16x16x32_bf16 v[100:103], v[150:153], v[186:189], v[100:103]
	v_mfma_f32_16x16x32_bf16 v[96:99], v[170:173], v[186:189], v[96:99]
	v_mfma_f32_16x16x32_bf16 v[84:87], v[150:153], v[194:197], v[84:87]
	v_mfma_f32_16x16x32_bf16 v[80:83], v[170:173], v[194:197], v[80:83]
	v_mfma_f32_16x16x32_bf16 v[68:71], v[150:153], v[202:205], v[68:71]
	v_mfma_f32_16x16x32_bf16 v[64:67], v[170:173], v[202:205], v[64:67]
	v_mfma_f32_16x16x32_bf16 v[116:119], v[166:169], v[182:185], v[116:119]
	v_mfma_f32_16x16x32_bf16 v[112:115], v[174:177], v[182:185], v[112:115]
	v_mfma_f32_16x16x32_bf16 v[100:103], v[166:169], v[190:193], v[100:103]
	v_mfma_f32_16x16x32_bf16 v[96:99], v[174:177], v[190:193], v[96:99]
	v_mfma_f32_16x16x32_bf16 v[84:87], v[166:169], v[198:201], v[84:87]
	v_mfma_f32_16x16x32_bf16 v[80:83], v[174:177], v[198:201], v[80:83]
	v_mfma_f32_16x16x32_bf16 v[68:71], v[166:169], v[206:209], v[68:71]
	v_mfma_f32_16x16x32_bf16 v[64:67], v[174:177], v[206:209], v[64:67]
	s_setprio 0
	s_barrier
	s_add_i32 s93, s93, s46
	v_lshl_add_u64 v[154:155], vcc, 0, v[156:157]
	s_mov_b32 m0, s93
	ds_read_b128 v[178:181], v241 offset:16384
	ds_read_b128 v[182:185], v241 offset:17408
	ds_read_b128 v[186:189], v241 offset:18432
	ds_read_b128 v[190:193], v241 offset:19456
	ds_read_b128 v[194:197], v241 offset:20480
	ds_read_b128 v[198:201], v241 offset:21504
	ds_read_b128 v[202:205], v241 offset:22528
	ds_read_b128 v[206:209], v241 offset:23552
	global_load_lds_dwordx4 v[154:155], off
	s_add_i32 m0, s93, 0x2000
	v_lshl_add_u64 v[162:163], vcc, 0, v[128:129]
	s_add_u32 vcc_lo, vcc_lo, s10
	s_addc_u32 vcc_hi, vcc_hi, s11
	s_add_i32 s37, s37, s46
	global_load_lds_dwordx4 v[162:163], off
	v_lshl_add_u64 v[210:211], vcc, 0, v[156:157]
	s_mov_b32 m0, s37
	v_lshl_add_u64 v[212:213], vcc, 0, v[128:129]
	global_load_lds_dwordx4 v[210:211], off
	s_add_i32 m0, s37, 0x2000
	v_lshl_add_u64 v[214:215], s[22:23], 0, v[156:157]
	global_load_lds_dwordx4 v[212:213], off
	s_mov_b32 m0, s47
	v_lshl_add_u64 v[216:217], s[22:23], 0, v[128:129]
	global_load_lds_dwordx4 v[214:215], off
	s_mov_b32 m0, s52
	s_nop 0
	global_load_lds_dwordx4 v[216:217], off
	s_waitcnt vmcnt(8)
	s_waitcnt lgkmcnt(0)
	s_barrier
; #define PG8_STAGE(bufoff, gbase, voff) do { _Pragma("unroll") for (int _i = 0; _i < 2; ++_i) \
;         __builtin_amdgcn_global_load_lds((const unsigned*)((const char*)(gbase) + (voff)[_i]), (PG8_LAS unsigned*)(lds + (bufoff) + ldsw + _i * 8192), 16, 0, 0); } while (0)
; #define PG8_LDA(dst, b, h) do { _Pragma("unroll") for (int m = 0; m < 4; ++m) _Pragma("unroll") for (int k = 0; k < 2; ++k) dst[m][k] = *(const PG8_LAS bf16x8*)(lds + PG8_SA(b, h) + aoff + m * 2048 + k * 1024); } while (0)
; #define PG8_LDB(dst, b, h) do { _Pragma("unroll") for (int n = 0; n < 2; ++n) _Pragma("unroll") for (int k = 0; k < 2; ++k) dst[n][k] = *(const PG8_LAS bf16x8*)(lds + PG8_SB(b, h) + boff + n * 2048 + k * 1024); } while (0)
; #define PG8_MMA(ai, bj, At, Bt) do { __builtin_amdgcn_s_setprio(1); _Pragma("unroll") for (int m = 0; m < 4; ++m) _Pragma("unroll") for (int n = 0; n < 2; ++n) _Pragma("unroll") for (int k = 0; k < 2; ++k) \
;         acc[ai][bj][m][n] = __builtin_amdgcn_mfma_f32_16x16x32_bf16(Bt[n][k], At[m][k], acc[ai][bj][m][n], 0, 0, 0); __builtin_amdgcn_s_setprio(0); } while (0)
; #define PG8_WAIT_V(n) asm volatile("s_waitcnt vmcnt(" #n ")" ::: "memory")
; #define PG8_WAIT_L(n) asm volatile("s_waitcnt lgkmcnt(" #n ")" ::: "memory")
; #define PG8_BAR __builtin_amdgcn_s_barrier()
; #define PG8_SCHED __builtin_amdgcn_sched_barrier(0)
; template <class Epi, class Sched, bool ALIGN_EPI = false, bool SP2 = false>
; __device__ __forceinline__ void gemm_phase(PG8_LAS unsigned char* lds, const Gemm g, const Sched& S, const Epi& E, int tid_in) {
;     ...
;             PG8_WAIT_V(8); PG8_WAIT_L(0); PG8_BAR; PG8_MMA(1, 0, At, B0); PG8_MMA(1, 1, At, B1); PG8_BAR; PG8_SCHED;
;             PG8_LDB(B0, 1, 0); PG8_LDB(B1, 1, 1); PG8_SCHED; PG8_LDA(At, 1, 0); PG8_STAGE(PG8_SA(0, 1), a2 + hstep, voffA);
;             PG8_WAIT_V(8); PG8_WAIT_L(0); PG8_BAR; PG8_MMA(0, 0, At, B0); PG8_MMA(0, 1, At, B1); PG8_BAR; PG8_SCHED;
	s_setprio 1
	v_mfma_f32_16x16x32_bf16 v[60:63], v[134:137], v[178:181], v[60:63]
	v_mfma_f32_16x16x32_bf16 v[56:59], v[142:145], v[178:181], v[56:59]
	v_mfma_f32_16x16x32_bf16 v[44:47], v[134:137], v[186:189], v[44:47]
	v_mfma_f32_16x16x32_bf16 v[40:43], v[142:145], v[186:189], v[40:43]
	v_mfma_f32_16x16x32_bf16 v[28:31], v[134:137], v[194:197], v[28:31]
	v_mfma_f32_16x16x32_bf16 v[24:27], v[142:145], v[194:197], v[24:27]
	v_mfma_f32_16x16x32_bf16 v[12:15], v[134:137], v[202:205], v[12:15]
	v_mfma_f32_16x16x32_bf16 v[8:11], v[142:145], v[202:205], v[8:11]
	v_mfma_f32_16x16x32_bf16 v[60:63], v[138:141], v[182:185], v[60:63]
	v_mfma_f32_16x16x32_bf16 v[56:59], v[146:149], v[182:185], v[56:59]
	v_mfma_f32_16x16x32_bf16 v[44:47], v[138:141], v[190:193], v[44:47]
	v_mfma_f32_16x16x32_bf16 v[40:43], v[146:149], v[190:193], v[40:43]
	v_mfma_f32_16x16x32_bf16 v[28:31], v[138:141], v[198:201], v[28:31]
	v_mfma_f32_16x16x32_bf16 v[24:27], v[146:149], v[198:201], v[24:27]
	v_mfma_f32_16x16x32_bf16 v[12:15], v[138:141], v[206:209], v[12:15]
	v_mfma_f32_16x16x32_bf16 v[8:11], v[146:149], v[206:209], v[8:11]
	s_setprio 0
	s_setprio 1
	v_mfma_f32_16x16x32_bf16 v[52:55], v[150:153], v[178:181], v[52:55]
	v_mfma_f32_16x16x32_bf16 v[48:51], v[170:173], v[178:181], v[48:51]
	v_mfma_f32_16x16x32_bf16 v[36:39], v[150:153], v[186:189], v[36:39]
	v_mfma_f32_16x16x32_bf16 v[32:35], v[170:173], v[186:189], v[32:35]
	v_mfma_f32_16x16x32_bf16 v[20:23], v[150:153], v[194:197], v[20:23]
	v_mfma_f32_16x16x32_bf16 v[16:19], v[170:173], v[194:197], v[16:19]
	v_mfma_f32_16x16x32_bf16 v[4:7], v[150:153], v[202:205], v[4:7]
	v_mfma_f32_16x16x32_bf16 v[0:3], v[170:173], v[202:205], v[0:3]
	v_mfma_f32_16x16x32_bf16 v[52:55], v[166:169], v[182:185], v[52:55]
	v_mfma_f32_16x16x32_bf16 v[48:51], v[174:177], v[182:185], v[48:51]
	v_mfma_f32_16x16x32_bf16 v[36:39], v[166:169], v[190:193], v[36:39]
	v_mfma_f32_16x16x32_bf16 v[32:35], v[174:177], v[190:193], v[32:35]
	v_mfma_f32_16x16x32_bf16 v[20:23], v[166:169], v[198:201], v[20:23]
	v_mfma_f32_16x16x32_bf16 v[16:19], v[174:177], v[198:201], v[16:19]
	v_mfma_f32_16x16x32_bf16 v[4:7], v[166:169], v[206:209], v[4:7]
	v_mfma_f32_16x16x32_bf16 v[0:3], v[174:177], v[206:209], v[0:3]
	s_setprio 0
	s_barrier
	s_add_i32 s37, 0, 0x18000
	s_add_i32 s93, 0, 0x1c000
	v_add_u32_e32 v146, s37, v237
	v_add_u32_e32 v174, s93, v237
	ds_read_b128 v[134:137], v146
	ds_read_b128 v[138:141], v146 offset:1024
	ds_read_b128 v[142:145], v146 offset:2048
	ds_read_b128 v[146:149], v146 offset:3072
	ds_read_b128 v[150:153], v174
	ds_read_b128 v[166:169], v174 offset:1024
	ds_read_b128 v[170:173], v174 offset:2048
	ds_read_b128 v[174:177], v174 offset:3072
	s_add_u32 s22, s22, s10
	s_addc_u32 s23, s23, s11
	s_mov_b32 m0, s53
	v_lshl_add_u64 v[218:219], s[22:23], 0, v[156:157]
	ds_read_b128 v[178:181], v241 offset:32768
	ds_read_b128 v[182:185], v241 offset:33792
	ds_read_b128 v[186:189], v241 offset:34816
	ds_read_b128 v[190:193], v241 offset:35840
	ds_read_b128 v[194:197], v241 offset:36864
	ds_read_b128 v[198:201], v241 offset:37888
	ds_read_b128 v[202:205], v241 offset:38912
	ds_read_b128 v[206:209], v241 offset:39936
	global_load_lds_dwordx4 v[218:219], off
	v_lshl_add_u64 v[218:219], s[22:23], 0, v[128:129]
	s_mov_b32 m0, s56
	s_nop 0
	global_load_lds_dwordx4 v[218:219], off
	s_waitcnt vmcnt(8)
	s_waitcnt lgkmcnt(0)
	s_barrier
	s_setprio 1
	v_mfma_f32_16x16x32_bf16 v[124:127], v[134:137], v[178:181], v[124:127]
	v_mfma_f32_16x16x32_bf16 v[120:123], v[142:145], v[178:181], v[120:123]
	v_mfma_f32_16x16x32_bf16 v[108:111], v[134:137], v[186:189], v[108:111]
	v_mfma_f32_16x16x32_bf16 v[104:107], v[142:145], v[186:189], v[104:107]
	v_mfma_f32_16x16x32_bf16 v[92:95], v[134:137], v[194:197], v[92:95]
	v_mfma_f32_16x16x32_bf16 v[88:91], v[142:145], v[194:197], v[88:91]
	v_mfma_f32_16x16x32_bf16 v[76:79], v[134:137], v[202:205], v[76:79]
	v_mfma_f32_16x16x32_bf16 v[72:75], v[142:145], v[202:205], v[72:75]
	v_mfma_f32_16x16x32_bf16 v[124:127], v[138:141], v[182:185], v[124:127]
	v_mfma_f32_16x16x32_bf16 v[120:123], v[146:149], v[182:185], v[120:123]
	v_mfma_f32_16x16x32_bf16 v[108:111], v[138:141], v[190:193], v[108:111]
	v_mfma_f32_16x16x32_bf16 v[104:107], v[146:149], v[190:193], v[104:107]
	v_mfma_f32_16x16x32_bf16 v[92:95], v[138:141], v[198:201], v[92:95]
	v_mfma_f32_16x16x32_bf16 v[88:91], v[146:149], v[198:201], v[88:91]
	v_mfma_f32_16x16x32_bf16 v[76:79], v[138:141], v[206:209], v[76:79]
	v_mfma_f32_16x16x32_bf16 v[72:75], v[146:149], v[206:209], v[72:75]
	s_setprio 0
	s_setprio 1
	v_mfma_f32_16x16x32_bf16 v[116:119], v[150:153], v[178:181], v[116:119]
	v_mfma_f32_16x16x32_bf16 v[112:115], v[170:173], v[178:181], v[112:115]
	v_mfma_f32_16x16x32_bf16 v[100:103], v[150:153], v[186:189], v[100:103]
	v_mfma_f32_16x16x32_bf16 v[96:99], v[170:173], v[186:189], v[96:99]
	v_mfma_f32_16x16x32_bf16 v[84:87], v[150:153], v[194:197], v[84:87]
	v_mfma_f32_16x16x32_bf16 v[80:83], v[170:173], v[194:197], v[80:83]
	v_mfma_f32_16x16x32_bf16 v[68:71], v[150:153], v[202:205], v[68:71]
	v_mfma_f32_16x16x32_bf16 v[64:67], v[170:173], v[202:205], v[64:67]
	v_mfma_f32_16x16x32_bf16 v[116:119], v[166:169], v[182:185], v[116:119]
	v_mfma_f32_16x16x32_bf16 v[112:115], v[174:177], v[182:185], v[112:115]
	v_mfma_f32_16x16x32_bf16 v[100:103], v[166:169], v[190:193], v[100:103]
	v_mfma_f32_16x16x32_bf16 v[96:99], v[174:177], v[190:193], v[96:99]
	v_mfma_f32_16x16x32_bf16 v[84:87], v[166:169], v[198:201], v[84:87]
	v_mfma_f32_16x16x32_bf16 v[80:83], v[174:177], v[198:201], v[80:83]
	v_mfma_f32_16x16x32_bf16 v[68:71], v[166:169], v[206:209], v[68:71]
	v_mfma_f32_16x16x32_bf16 v[64:67], v[174:177], v[206:209], v[64:67]
	s_setprio 0
	s_barrier
; #define PG8_STAGE(bufoff, gbase, voff) do { _Pragma("unroll") for (int _i = 0; _i < 2; ++_i) \
;         __builtin_amdgcn_global_load_lds((const unsigned*)((const char*)(gbase) + (voff)[_i]), (PG8_LAS unsigned*)(lds + (bufoff) + ldsw + _i * 8192), 16, 0, 0); } while (0)
; #define PG8_LDA(dst, b, h) do { _Pragma("unroll") for (int m = 0; m < 4; ++m) _Pragma("unroll") for (int k = 0; k < 2; ++k) dst[m][k] = *(const PG8_LAS bf16x8*)(lds + PG8_SA(b, h) + aoff + m * 2048 + k * 1024); } while (0)
; #define PG8_MMA(ai, bj, At, Bt) do { __builtin_amdgcn_s_setprio(1); _Pragma("unroll") for (int m = 0; m < 4; ++m) _Pragma("unroll") for (int n = 0; n < 2; ++n) _Pragma("unroll") for (int k = 0; k < 2; ++k) \
;         acc[ai][bj][m][n] = __builtin_amdgcn_mfma_f32_16x16x32_bf16(Bt[n][k], At[m][k], acc[ai][bj][m][n], 0, 0, 0); __builtin_amdgcn_s_setprio(0); } while (0)
; #define PG8_WAIT_V(n) asm volatile("s_waitcnt vmcnt(" #n ")" ::: "memory")
; #define PG8_WAIT_L(n) asm volatile("s_waitcnt lgkmcnt(" #n ")" ::: "memory")
; #define PG8_BAR __builtin_amdgcn_s_barrier()
; #define PG8_SCHED __builtin_amdgcn_sched_barrier(0)
; template <class Epi, class Sched, bool ALIGN_EPI = false, bool SP2 = false>
; __device__ __forceinline__ void gemm_phase(PG8_LAS unsigned char* lds, const Gemm g, const Sched& S, const Epi& E, int tid_in) {
;     ...
;         for (int t = 0; t < nt; t += 2) {
;             const bool last = (t == nt - 2);
;             const char* a1 = cA + (size_t)(t + 1) * kstep;
;             const char* a2 = last ? nA : cA + (size_t)(t + 2) * kstep; const char* b2 = last ? nB : cB + (size_t)(t + 2) * kstep;
;             const char* a3 = a2 + kstep; const char* b3 = b2 + kstep;
;     ...
;             PG8_LDA(At, 1, 1); PG8_STAGE(PG8_SB(1, 0), b3, voffB); PG8_STAGE(PG8_SB(1, 1), b3 + hstep, voffB); PG8_STAGE(PG8_SA(1, 0), a3, voffA);
;             PG8_WAIT_V(8); PG8_WAIT_L(0); PG8_BAR; PG8_MMA(1, 0, At, B0); PG8_MMA(1, 1, At, B1); PG8_BAR; PG8_SCHED;
	s_add_i32 s22, s37, s46
	v_lshl_add_u64 v[154:155], v[154:155], 0, s[64:65]
	s_mov_b32 m0, s22
	ds_read_b128 v[178:181], v241 offset:49152
	ds_read_b128 v[182:185], v241 offset:50176
	ds_read_b128 v[186:189], v241 offset:51200
	ds_read_b128 v[190:193], v241 offset:52224
	ds_read_b128 v[194:197], v241 offset:53248
	ds_read_b128 v[198:201], v241 offset:54272
	ds_read_b128 v[202:205], v241 offset:55296
	ds_read_b128 v[206:209], v241 offset:56320
	global_load_lds_dwordx4 v[154:155], off
	v_lshl_add_u64 v[154:155], v[162:163], 0, s[64:65]
	s_add_i32 m0, s22, 0x2000
	s_add_i32 s22, s93, s46
	global_load_lds_dwordx4 v[154:155], off
	v_lshl_add_u64 v[154:155], v[210:211], 0, s[64:65]
	s_mov_b32 m0, s22
	s_nop 0
	global_load_lds_dwordx4 v[154:155], off
	v_lshl_add_u64 v[154:155], v[212:213], 0, s[64:65]
	s_add_i32 m0, s22, 0x2000
	s_nop 0
	global_load_lds_dwordx4 v[154:155], off
	v_lshl_add_u64 v[154:155], v[214:215], 0, s[64:65]
	s_mov_b32 m0, s66
	s_nop 0
	global_load_lds_dwordx4 v[154:155], off
	v_lshl_add_u64 v[154:155], v[216:217], 0, s[64:65]
	s_mov_b32 m0, s67
	s_nop 0
	global_load_lds_dwordx4 v[154:155], off
	s_waitcnt vmcnt(8)
	s_waitcnt lgkmcnt(0)
	s_barrier
	s_setprio 1
	v_mfma_f32_16x16x32_bf16 v[60:63], v[134:137], v[178:181], v[60:63]
	v_mfma_f32_16x16x32_bf16 v[56:59], v[142:145], v[178:181], v[56:59]
	v_mfma_f32_16x16x32_bf16 v[44:47], v[134:137], v[186:189], v[44:47]
	v_mfma_f32_16x16x32_bf16 v[40:43], v[142:145], v[186:189], v[40:43]
	v_mfma_f32_16x16x32_bf16 v[28:31], v[134:137], v[194:197], v[28:31]
	v_mfma_f32_16x16x32_bf16 v[24:27], v[142:145], v[194:197], v[24:27]
	v_mfma_f32_16x16x32_bf16 v[12:15], v[134:137], v[202:205], v[12:15]
	v_mfma_f32_16x16x32_bf16 v[8:11], v[142:145], v[202:205], v[8:11]
	v_mfma_f32_16x16x32_bf16 v[60:63], v[138:141], v[182:185], v[60:63]
	v_mfma_f32_16x16x32_bf16 v[56:59], v[146:149], v[182:185], v[56:59]
	v_mfma_f32_16x16x32_bf16 v[44:47], v[138:141], v[190:193], v[44:47]
	v_mfma_f32_16x16x32_bf16 v[40:43], v[146:149], v[190:193], v[40:43]
	v_mfma_f32_16x16x32_bf16 v[28:31], v[138:141], v[198:201], v[28:31]
	v_mfma_f32_16x16x32_bf16 v[24:27], v[146:149], v[198:201], v[24:27]
	v_mfma_f32_16x16x32_bf16 v[12:15], v[138:141], v[206:209], v[12:15]
	v_mfma_f32_16x16x32_bf16 v[8:11], v[146:149], v[206:209], v[8:11]
	s_setprio 0
	s_setprio 1
	v_mfma_f32_16x16x32_bf16 v[52:55], v[150:153], v[178:181], v[52:55]
	v_mfma_f32_16x16x32_bf16 v[48:51], v[170:173], v[178:181], v[48:51]
	v_mfma_f32_16x16x32_bf16 v[36:39], v[150:153], v[186:189], v[36:39]
	v_mfma_f32_16x16x32_bf16 v[32:35], v[170:173], v[186:189], v[32:35]
	v_mfma_f32_16x16x32_bf16 v[20:23], v[150:153], v[194:197], v[20:23]
	v_mfma_f32_16x16x32_bf16 v[16:19], v[170:173], v[194:197], v[16:19]
	v_mfma_f32_16x16x32_bf16 v[4:7], v[150:153], v[202:205], v[4:7]
	v_mfma_f32_16x16x32_bf16 v[0:3], v[170:173], v[202:205], v[0:3]
	v_mfma_f32_16x16x32_bf16 v[52:55], v[166:169], v[182:185], v[52:55]
	v_mfma_f32_16x16x32_bf16 v[48:51], v[174:177], v[182:185], v[48:51]
	v_mfma_f32_16x16x32_bf16 v[36:39], v[166:169], v[190:193], v[36:39]
	v_mfma_f32_16x16x32_bf16 v[32:35], v[174:177], v[190:193], v[32:35]
	v_mfma_f32_16x16x32_bf16 v[20:23], v[166:169], v[198:201], v[20:23]
	v_mfma_f32_16x16x32_bf16 v[16:19], v[174:177], v[198:201], v[16:19]
	v_mfma_f32_16x16x32_bf16 v[4:7], v[166:169], v[206:209], v[4:7]
	v_mfma_f32_16x16x32_bf16 v[0:3], v[174:177], v[206:209], v[0:3]
	s_setprio 0
	s_barrier
	s_add_u32 s0, s0, 0x100
	s_addc_u32 s1, s1, 0
	s_add_u32 s55, s55, 0x100
	s_addc_u32 s92, s92, 0
	s_cmp_ge_i32 s36, s63
	s_mov_b32 s22, s36
	s_cbranch_scc0 .LBB0_1024
